# tail-slot weight transposer processes two items per iteration (64 loads in flight per wave)
# speedup vs baseline: 1.0519x; 1.0040x over previous
; #define LAS __attribute__((address_space(3)))
; __device__ __forceinline__ void transpose_item(const float* W, int K, int N, bf16_t* WT, int n0src, int n0dst, int k0, LAS float* scr, int lane) {
;     float v[32];
; #pragma unroll
;     for (int i = 0; i < 32; ++i) { const int kk = 2 * i + (lane >> 5); v[i] = W[(size_t)(k0 + kk) * N + n0src + (lane & 31)]; }
; #pragma unroll
;     for (int i = 0; i < 32; ++i) { const int kk = 2 * i + (lane >> 5); scr[kk * 33 + (lane & 31)] = v[i]; }
.Ltr_loop_a0:
	s_add_i32 s40, s98, 0x400
	s_cmpk_ge_u32 s40, 0x580
	s_cbranch_scc1 .Ltr_single_a0
	s_lshr_b32 s100, s98, 5
	s_and_b32 s101, s98, 31
	s_lshl_b32 s0, s100, 18
	s_lshl_b32 s1, s101, 7
	s_add_u32 s0, s0, s1
	s_add_u32 s0, s32, s0
	s_addc_u32 s1, s33, 0
	global_load_dword v32, v23, s[0:1] nt
	s_add_u32 s0, s0, 0x2000
	s_addc_u32 s1, s1, 0
	global_load_dword v33, v23, s[0:1] nt
	s_add_u32 s0, s0, 0x2000
	s_addc_u32 s1, s1, 0
	global_load_dword v34, v23, s[0:1] nt
	s_add_u32 s0, s0, 0x2000
	s_addc_u32 s1, s1, 0
	global_load_dword v35, v23, s[0:1] nt
	s_add_u32 s0, s0, 0x2000
	s_addc_u32 s1, s1, 0
	global_load_dword v36, v23, s[0:1] nt
	s_add_u32 s0, s0, 0x2000
	s_addc_u32 s1, s1, 0
	global_load_dword v37, v23, s[0:1] nt
	s_add_u32 s0, s0, 0x2000
	s_addc_u32 s1, s1, 0
	global_load_dword v38, v23, s[0:1] nt
	s_add_u32 s0, s0, 0x2000
	s_addc_u32 s1, s1, 0
	global_load_dword v39, v23, s[0:1] nt
	s_add_u32 s0, s0, 0x2000
	s_addc_u32 s1, s1, 0
	global_load_dword v40, v23, s[0:1] nt
	s_add_u32 s0, s0, 0x2000
	s_addc_u32 s1, s1, 0
	global_load_dword v41, v23, s[0:1] nt
	s_add_u32 s0, s0, 0x2000
	s_addc_u32 s1, s1, 0
	global_load_dword v42, v23, s[0:1] nt
	s_add_u32 s0, s0, 0x2000
	s_addc_u32 s1, s1, 0
	global_load_dword v43, v23, s[0:1] nt
	s_add_u32 s0, s0, 0x2000
	s_addc_u32 s1, s1, 0
	global_load_dword v44, v23, s[0:1] nt
	s_add_u32 s0, s0, 0x2000
	s_addc_u32 s1, s1, 0
	global_load_dword v45, v23, s[0:1] nt
	s_add_u32 s0, s0, 0x2000
	s_addc_u32 s1, s1, 0
	global_load_dword v46, v23, s[0:1] nt
	s_add_u32 s0, s0, 0x2000
	s_addc_u32 s1, s1, 0
	global_load_dword v47, v23, s[0:1] nt
	s_add_u32 s0, s0, 0x2000
	s_addc_u32 s1, s1, 0
	global_load_dword v48, v23, s[0:1] nt
	s_add_u32 s0, s0, 0x2000
	s_addc_u32 s1, s1, 0
	global_load_dword v49, v23, s[0:1] nt
	s_add_u32 s0, s0, 0x2000
	s_addc_u32 s1, s1, 0
	global_load_dword v50, v23, s[0:1] nt
	s_add_u32 s0, s0, 0x2000
	s_addc_u32 s1, s1, 0
	global_load_dword v51, v23, s[0:1] nt
	s_add_u32 s0, s0, 0x2000
	s_addc_u32 s1, s1, 0
	global_load_dword v52, v23, s[0:1] nt
	s_add_u32 s0, s0, 0x2000
	s_addc_u32 s1, s1, 0
	global_load_dword v53, v23, s[0:1] nt
	s_add_u32 s0, s0, 0x2000
	s_addc_u32 s1, s1, 0
	global_load_dword v54, v23, s[0:1] nt
	s_add_u32 s0, s0, 0x2000
	s_addc_u32 s1, s1, 0
	global_load_dword v55, v23, s[0:1] nt
	s_add_u32 s0, s0, 0x2000
	s_addc_u32 s1, s1, 0
	global_load_dword v56, v23, s[0:1] nt
	s_add_u32 s0, s0, 0x2000
	s_addc_u32 s1, s1, 0
	global_load_dword v57, v23, s[0:1] nt
	s_add_u32 s0, s0, 0x2000
	s_addc_u32 s1, s1, 0
	global_load_dword v58, v23, s[0:1] nt
	s_add_u32 s0, s0, 0x2000
	s_addc_u32 s1, s1, 0
	global_load_dword v59, v23, s[0:1] nt
	s_add_u32 s0, s0, 0x2000
	s_addc_u32 s1, s1, 0
	global_load_dword v60, v23, s[0:1] nt
	s_add_u32 s0, s0, 0x2000
	s_addc_u32 s1, s1, 0
	global_load_dword v61, v23, s[0:1] nt
	s_add_u32 s0, s0, 0x2000
	s_addc_u32 s1, s1, 0
	global_load_dword v62, v23, s[0:1] nt
	s_add_u32 s0, s0, 0x2000
	s_addc_u32 s1, s1, 0
	global_load_dword v63, v23, s[0:1] nt
	s_lshr_b32 s41, s40, 5
	s_and_b32 s42, s40, 31
	s_lshl_b32 s0, s41, 18
	s_lshl_b32 s1, s42, 7
	s_add_u32 s0, s0, s1
	s_add_u32 s0, s32, s0
	s_addc_u32 s1, s33, 0
	global_load_dword v112, v23, s[0:1] nt
	s_add_u32 s0, s0, 0x2000
	s_addc_u32 s1, s1, 0
	global_load_dword v113, v23, s[0:1] nt
	s_add_u32 s0, s0, 0x2000
	s_addc_u32 s1, s1, 0
	global_load_dword v114, v23, s[0:1] nt
	s_add_u32 s0, s0, 0x2000
	s_addc_u32 s1, s1, 0
	global_load_dword v115, v23, s[0:1] nt
	s_add_u32 s0, s0, 0x2000
	s_addc_u32 s1, s1, 0
	global_load_dword v116, v23, s[0:1] nt
	s_add_u32 s0, s0, 0x2000
	s_addc_u32 s1, s1, 0
	global_load_dword v117, v23, s[0:1] nt
	s_add_u32 s0, s0, 0x2000
	s_addc_u32 s1, s1, 0
	global_load_dword v118, v23, s[0:1] nt
	s_add_u32 s0, s0, 0x2000
	s_addc_u32 s1, s1, 0
	global_load_dword v119, v23, s[0:1] nt
	s_add_u32 s0, s0, 0x2000
	s_addc_u32 s1, s1, 0
	global_load_dword v120, v23, s[0:1] nt
	s_add_u32 s0, s0, 0x2000
	s_addc_u32 s1, s1, 0
	global_load_dword v121, v23, s[0:1] nt
	s_add_u32 s0, s0, 0x2000
	s_addc_u32 s1, s1, 0
	global_load_dword v122, v23, s[0:1] nt
	s_add_u32 s0, s0, 0x2000
	s_addc_u32 s1, s1, 0
	global_load_dword v123, v23, s[0:1] nt
	s_add_u32 s0, s0, 0x2000
	s_addc_u32 s1, s1, 0
	global_load_dword v124, v23, s[0:1] nt
	s_add_u32 s0, s0, 0x2000
	s_addc_u32 s1, s1, 0
	global_load_dword v125, v23, s[0:1] nt
	s_add_u32 s0, s0, 0x2000
	s_addc_u32 s1, s1, 0
	global_load_dword v126, v23, s[0:1] nt
	s_add_u32 s0, s0, 0x2000
	s_addc_u32 s1, s1, 0
	global_load_dword v127, v23, s[0:1] nt
	s_add_u32 s0, s0, 0x2000
	s_addc_u32 s1, s1, 0
	global_load_dword v128, v23, s[0:1] nt
	s_add_u32 s0, s0, 0x2000
	s_addc_u32 s1, s1, 0
	global_load_dword v129, v23, s[0:1] nt
	s_add_u32 s0, s0, 0x2000
	s_addc_u32 s1, s1, 0
	global_load_dword v130, v23, s[0:1] nt
	s_add_u32 s0, s0, 0x2000
	s_addc_u32 s1, s1, 0
	global_load_dword v131, v23, s[0:1] nt
	s_add_u32 s0, s0, 0x2000
	s_addc_u32 s1, s1, 0
	global_load_dword v132, v23, s[0:1] nt
	s_add_u32 s0, s0, 0x2000
	s_addc_u32 s1, s1, 0
	global_load_dword v133, v23, s[0:1] nt
	s_add_u32 s0, s0, 0x2000
	s_addc_u32 s1, s1, 0
	global_load_dword v134, v23, s[0:1] nt
	s_add_u32 s0, s0, 0x2000
	s_addc_u32 s1, s1, 0
	global_load_dword v135, v23, s[0:1] nt
	s_add_u32 s0, s0, 0x2000
	s_addc_u32 s1, s1, 0
	global_load_dword v136, v23, s[0:1] nt
	s_add_u32 s0, s0, 0x2000
	s_addc_u32 s1, s1, 0
	global_load_dword v137, v23, s[0:1] nt
	s_add_u32 s0, s0, 0x2000
	s_addc_u32 s1, s1, 0
	global_load_dword v138, v23, s[0:1] nt
	s_add_u32 s0, s0, 0x2000
	s_addc_u32 s1, s1, 0
	global_load_dword v139, v23, s[0:1] nt
	s_add_u32 s0, s0, 0x2000
	s_addc_u32 s1, s1, 0
	global_load_dword v140, v23, s[0:1] nt
	s_add_u32 s0, s0, 0x2000
	s_addc_u32 s1, s1, 0
	global_load_dword v141, v23, s[0:1] nt
	s_add_u32 s0, s0, 0x2000
	s_addc_u32 s1, s1, 0
	global_load_dword v142, v23, s[0:1] nt
	s_add_u32 s0, s0, 0x2000
	s_addc_u32 s1, s1, 0
	global_load_dword v143, v23, s[0:1] nt
	s_waitcnt vmcnt(63)
; #define LAS __attribute__((address_space(3)))
; __device__ __forceinline__ unsigned cvt_pk_bf16(float lo, float hi) { unsigned r; asm volatile("v_cvt_pk_bf16_f32 %0, %1, %2" : "=v"(r) : "v"(lo), "v"(hi)); return r; }
; #define ST16(grp, p, v) do { if ((NTG >> (grp)) & 1) NT16(p, v); else PL16(p, v); } while (0)
; __device__ __forceinline__ void transpose_item(const float* W, int K, int N, bf16_t* WT, int n0src, int n0dst, int k0, LAS float* scr, int lane) {
;     ...
;     for (int i = 0; i < 32; ++i) { const int kk = 2 * i + (lane >> 5); v[i] = W[(size_t)(k0 + kk) * N + n0src + (lane & 31)]; }
; #pragma unroll
;     for (int i = 0; i < 32; ++i) { const int kk = 2 * i + (lane >> 5); scr[kk * 33 + (lane & 31)] = v[i]; }
;     asm volatile("s_waitcnt lgkmcnt(0)" ::: "memory");
;     const int c = lane & 7;
; #pragma unroll
;     for (int j = 0; j < 4; ++j) { const int n = (lane >> 3) + 8 * j; const LAS float* s = scr + (8 * c) * 33 + n;
;         u32x4 o; o.x = cvt_pk_bf16(s[0 * 33], s[1 * 33]); o.y = cvt_pk_bf16(s[2 * 33], s[3 * 33]); o.z = cvt_pk_bf16(s[4 * 33], s[5 * 33]); o.w = cvt_pk_bf16(s[6 * 33], s[7 * 33]);
;         ST16(6, WT + (size_t)(n0dst + n) * K + k0 + 8 * c, o); }
	ds_write_b32 v19, v32
	s_waitcnt vmcnt(62)
	ds_write_b32 v19, v33 offset:264
	s_waitcnt vmcnt(61)
	ds_write_b32 v19, v34 offset:528
	s_waitcnt vmcnt(60)
	ds_write_b32 v19, v35 offset:792
	s_waitcnt vmcnt(59)
	ds_write_b32 v19, v36 offset:1056
	s_waitcnt vmcnt(58)
	ds_write_b32 v19, v37 offset:1320
	s_waitcnt vmcnt(57)
	ds_write_b32 v19, v38 offset:1584
	s_waitcnt vmcnt(56)
	ds_write_b32 v19, v39 offset:1848
	s_waitcnt vmcnt(55)
	ds_write_b32 v19, v40 offset:2112
	s_waitcnt vmcnt(54)
	ds_write_b32 v19, v41 offset:2376
	s_waitcnt vmcnt(53)
	ds_write_b32 v19, v42 offset:2640
	s_waitcnt vmcnt(52)
	ds_write_b32 v19, v43 offset:2904
	s_waitcnt vmcnt(51)
	ds_write_b32 v19, v44 offset:3168
	s_waitcnt vmcnt(50)
	ds_write_b32 v19, v45 offset:3432
	s_waitcnt vmcnt(49)
	ds_write_b32 v19, v46 offset:3696
	s_waitcnt vmcnt(48)
	ds_write_b32 v19, v47 offset:3960
	s_waitcnt vmcnt(47)
	ds_write_b32 v19, v48 offset:4224
	s_waitcnt vmcnt(46)
	ds_write_b32 v19, v49 offset:4488
	s_waitcnt vmcnt(45)
	ds_write_b32 v19, v50 offset:4752
	s_waitcnt vmcnt(44)
	ds_write_b32 v19, v51 offset:5016
	s_waitcnt vmcnt(43)
	ds_write_b32 v19, v52 offset:5280
	s_waitcnt vmcnt(42)
	ds_write_b32 v19, v53 offset:5544
	s_waitcnt vmcnt(41)
	ds_write_b32 v19, v54 offset:5808
	s_waitcnt vmcnt(40)
	ds_write_b32 v19, v55 offset:6072
	s_waitcnt vmcnt(39)
	ds_write_b32 v19, v56 offset:6336
	s_waitcnt vmcnt(38)
	ds_write_b32 v19, v57 offset:6600
	s_waitcnt vmcnt(37)
	ds_write_b32 v19, v58 offset:6864
	s_waitcnt vmcnt(36)
	ds_write_b32 v19, v59 offset:7128
	s_waitcnt vmcnt(35)
	ds_write_b32 v19, v60 offset:7392
	s_waitcnt vmcnt(34)
	ds_write_b32 v19, v61 offset:7656
	s_waitcnt vmcnt(33)
	ds_write_b32 v19, v62 offset:7920
	s_waitcnt vmcnt(32)
	ds_write_b32 v19, v63 offset:8184
	s_mul_i32 s0, s101, 0x2c000
	s_lshl_b32 s1, s100, 7
	s_add_u32 s0, s0, s1
	s_add_u32 s0, s34, s0
	s_addc_u32 s1, s35, 0
	s_waitcnt lgkmcnt(0)
	ds_read_b32 v64, v22
	ds_read_b32 v65, v22 offset:132
	ds_read_b32 v66, v22 offset:264
	ds_read_b32 v67, v22 offset:396
	ds_read_b32 v68, v22 offset:528
	ds_read_b32 v69, v22 offset:660
	ds_read_b32 v70, v22 offset:792
	ds_read_b32 v71, v22 offset:924
	ds_read_b32 v72, v22 offset:32
	ds_read_b32 v73, v22 offset:164
	ds_read_b32 v74, v22 offset:296
	ds_read_b32 v75, v22 offset:428
	ds_read_b32 v76, v22 offset:560
	ds_read_b32 v77, v22 offset:692
	ds_read_b32 v78, v22 offset:824
	ds_read_b32 v79, v22 offset:956
	ds_read_b32 v80, v22 offset:64
	ds_read_b32 v81, v22 offset:196
	ds_read_b32 v82, v22 offset:328
	ds_read_b32 v83, v22 offset:460
	ds_read_b32 v84, v22 offset:592
	ds_read_b32 v85, v22 offset:724
	ds_read_b32 v86, v22 offset:856
	ds_read_b32 v87, v22 offset:988
	ds_read_b32 v88, v22 offset:96
	ds_read_b32 v89, v22 offset:228
	ds_read_b32 v90, v22 offset:360
	ds_read_b32 v91, v22 offset:492
	ds_read_b32 v92, v22 offset:624
	ds_read_b32 v93, v22 offset:756
	ds_read_b32 v94, v22 offset:888
	ds_read_b32 v95, v22 offset:1020
	s_waitcnt lgkmcnt(15)
	v_cvt_pk_bf16_f32 v96, v64, v65
	v_cvt_pk_bf16_f32 v97, v66, v67
	v_cvt_pk_bf16_f32 v98, v68, v69
	v_cvt_pk_bf16_f32 v99, v70, v71
	global_store_dwordx4 v24, v[96:99], s[0:1]
	s_add_u32 s0, s0, 0xb000
	s_addc_u32 s1, s1, 0
	s_waitcnt lgkmcnt(15)
	v_cvt_pk_bf16_f32 v100, v72, v73
	v_cvt_pk_bf16_f32 v101, v74, v75
	v_cvt_pk_bf16_f32 v102, v76, v77
	v_cvt_pk_bf16_f32 v103, v78, v79
	global_store_dwordx4 v24, v[100:103], s[0:1]
	s_add_u32 s0, s0, 0xb000
	s_addc_u32 s1, s1, 0
	s_waitcnt lgkmcnt(8)
	v_cvt_pk_bf16_f32 v104, v80, v81
	v_cvt_pk_bf16_f32 v105, v82, v83
	v_cvt_pk_bf16_f32 v106, v84, v85
	v_cvt_pk_bf16_f32 v107, v86, v87
	global_store_dwordx4 v24, v[104:107], s[0:1]
	s_add_u32 s0, s0, 0xb000
	s_addc_u32 s1, s1, 0
	s_waitcnt lgkmcnt(0)
	v_cvt_pk_bf16_f32 v108, v88, v89
	v_cvt_pk_bf16_f32 v109, v90, v91
	v_cvt_pk_bf16_f32 v110, v92, v93
	v_cvt_pk_bf16_f32 v111, v94, v95
	global_store_dwordx4 v24, v[108:111], s[0:1]
	s_waitcnt vmcnt(31)
	ds_write_b32 v19, v112
	s_waitcnt vmcnt(30)
	ds_write_b32 v19, v113 offset:264
	s_waitcnt vmcnt(29)
	ds_write_b32 v19, v114 offset:528
	s_waitcnt vmcnt(28)
	ds_write_b32 v19, v115 offset:792
	s_waitcnt vmcnt(27)
	ds_write_b32 v19, v116 offset:1056
	s_waitcnt vmcnt(26)
	ds_write_b32 v19, v117 offset:1320
	s_waitcnt vmcnt(25)
	ds_write_b32 v19, v118 offset:1584
	s_waitcnt vmcnt(24)
	ds_write_b32 v19, v119 offset:1848
	s_waitcnt vmcnt(23)
	ds_write_b32 v19, v120 offset:2112
	s_waitcnt vmcnt(22)
	ds_write_b32 v19, v121 offset:2376
	s_waitcnt vmcnt(21)
	ds_write_b32 v19, v122 offset:2640
	s_waitcnt vmcnt(20)
	ds_write_b32 v19, v123 offset:2904
	s_waitcnt vmcnt(19)
	ds_write_b32 v19, v124 offset:3168
	s_waitcnt vmcnt(18)
	ds_write_b32 v19, v125 offset:3432
	s_waitcnt vmcnt(17)
	ds_write_b32 v19, v126 offset:3696
	s_waitcnt vmcnt(16)
	ds_write_b32 v19, v127 offset:3960
	s_waitcnt vmcnt(15)
	ds_write_b32 v19, v128 offset:4224
	s_waitcnt vmcnt(14)
	ds_write_b32 v19, v129 offset:4488
	s_waitcnt vmcnt(13)
	ds_write_b32 v19, v130 offset:4752
	s_waitcnt vmcnt(12)
	ds_write_b32 v19, v131 offset:5016
	s_waitcnt vmcnt(11)
	ds_write_b32 v19, v132 offset:5280
	s_waitcnt vmcnt(10)
	ds_write_b32 v19, v133 offset:5544
	s_waitcnt vmcnt(9)
	ds_write_b32 v19, v134 offset:5808
	s_waitcnt vmcnt(8)
	ds_write_b32 v19, v135 offset:6072
	s_waitcnt vmcnt(7)
	ds_write_b32 v19, v136 offset:6336
	s_waitcnt vmcnt(6)
	ds_write_b32 v19, v137 offset:6600
	s_waitcnt vmcnt(5)
	ds_write_b32 v19, v138 offset:6864
	s_waitcnt vmcnt(4)
	ds_write_b32 v19, v139 offset:7128
	s_waitcnt vmcnt(3)
	ds_write_b32 v19, v140 offset:7392
	s_waitcnt vmcnt(2)
	ds_write_b32 v19, v141 offset:7656
	s_waitcnt vmcnt(1)
	ds_write_b32 v19, v142 offset:7920
	s_waitcnt vmcnt(0)
; #define LAS __attribute__((address_space(3)))
; __device__ __forceinline__ unsigned cvt_pk_bf16(float lo, float hi) { unsigned r; asm volatile("v_cvt_pk_bf16_f32 %0, %1, %2" : "=v"(r) : "v"(lo), "v"(hi)); return r; }
; #define ST16(grp, p, v) do { if ((NTG >> (grp)) & 1) NT16(p, v); else PL16(p, v); } while (0)
; __device__ __forceinline__ void transpose_item(const float* W, int K, int N, bf16_t* WT, int n0src, int n0dst, int k0, LAS float* scr, int lane) {
;     ...
;     asm volatile("s_waitcnt lgkmcnt(0)" ::: "memory");
;     const int c = lane & 7;
; #pragma unroll
;     for (int j = 0; j < 4; ++j) { const int n = (lane >> 3) + 8 * j; const LAS float* s = scr + (8 * c) * 33 + n;
;         u32x4 o; o.x = cvt_pk_bf16(s[0 * 33], s[1 * 33]); o.y = cvt_pk_bf16(s[2 * 33], s[3 * 33]); o.z = cvt_pk_bf16(s[4 * 33], s[5 * 33]); o.w = cvt_pk_bf16(s[6 * 33], s[7 * 33]);
;         ST16(6, WT + (size_t)(n0dst + n) * K + k0 + 8 * c, o); }
;     asm volatile("s_waitcnt lgkmcnt(0)" ::: "memory");
; }
	ds_write_b32 v19, v143 offset:8184
	s_mul_i32 s0, s42, 0x2c000
	s_lshl_b32 s1, s41, 7
	s_add_u32 s0, s0, s1
	s_add_u32 s0, s34, s0
	s_addc_u32 s1, s35, 0
	s_waitcnt lgkmcnt(0)
	ds_read_b32 v64, v22
	ds_read_b32 v65, v22 offset:132
	ds_read_b32 v66, v22 offset:264
	ds_read_b32 v67, v22 offset:396
	ds_read_b32 v68, v22 offset:528
	ds_read_b32 v69, v22 offset:660
	ds_read_b32 v70, v22 offset:792
	ds_read_b32 v71, v22 offset:924
	ds_read_b32 v72, v22 offset:32
	ds_read_b32 v73, v22 offset:164
	ds_read_b32 v74, v22 offset:296
	ds_read_b32 v75, v22 offset:428
	ds_read_b32 v76, v22 offset:560
	ds_read_b32 v77, v22 offset:692
	ds_read_b32 v78, v22 offset:824
	ds_read_b32 v79, v22 offset:956
	ds_read_b32 v80, v22 offset:64
	ds_read_b32 v81, v22 offset:196
	ds_read_b32 v82, v22 offset:328
	ds_read_b32 v83, v22 offset:460
	ds_read_b32 v84, v22 offset:592
	ds_read_b32 v85, v22 offset:724
	ds_read_b32 v86, v22 offset:856
	ds_read_b32 v87, v22 offset:988
	ds_read_b32 v88, v22 offset:96
	ds_read_b32 v89, v22 offset:228
	ds_read_b32 v90, v22 offset:360
	ds_read_b32 v91, v22 offset:492
	ds_read_b32 v92, v22 offset:624
	ds_read_b32 v93, v22 offset:756
	ds_read_b32 v94, v22 offset:888
	ds_read_b32 v95, v22 offset:1020
	s_waitcnt lgkmcnt(15)
	v_cvt_pk_bf16_f32 v96, v64, v65
	v_cvt_pk_bf16_f32 v97, v66, v67
	v_cvt_pk_bf16_f32 v98, v68, v69
	v_cvt_pk_bf16_f32 v99, v70, v71
	global_store_dwordx4 v24, v[96:99], s[0:1]
	s_add_u32 s0, s0, 0xb000
	s_addc_u32 s1, s1, 0
	s_waitcnt lgkmcnt(15)
	v_cvt_pk_bf16_f32 v100, v72, v73
	v_cvt_pk_bf16_f32 v101, v74, v75
	v_cvt_pk_bf16_f32 v102, v76, v77
	v_cvt_pk_bf16_f32 v103, v78, v79
	global_store_dwordx4 v24, v[100:103], s[0:1]
	s_add_u32 s0, s0, 0xb000
	s_addc_u32 s1, s1, 0
	s_waitcnt lgkmcnt(8)
	v_cvt_pk_bf16_f32 v104, v80, v81
	v_cvt_pk_bf16_f32 v105, v82, v83
	v_cvt_pk_bf16_f32 v106, v84, v85
	v_cvt_pk_bf16_f32 v107, v86, v87
	global_store_dwordx4 v24, v[104:107], s[0:1]
	s_add_u32 s0, s0, 0xb000
	s_addc_u32 s1, s1, 0
	s_waitcnt lgkmcnt(0)
	v_cvt_pk_bf16_f32 v108, v88, v89
	v_cvt_pk_bf16_f32 v109, v90, v91
	v_cvt_pk_bf16_f32 v110, v92, v93
	v_cvt_pk_bf16_f32 v111, v94, v95
	global_store_dwordx4 v24, v[108:111], s[0:1]
	s_add_i32 s98, s98, 0x800
	s_cmpk_lt_u32 s98, 0x580
	s_cbranch_scc1 .Ltr_loop_a0
	s_branch .Ltr_end_a0
.Ltr_single_a0:
	s_lshr_b32 s100, s98, 5
	s_and_b32 s101, s98, 31
	s_lshl_b32 s0, s100, 18
	s_lshl_b32 s1, s101, 7
	s_add_u32 s0, s0, s1
	s_add_u32 s0, s32, s0
	s_addc_u32 s1, s33, 0
	global_load_dword v32, v23, s[0:1] nt
	s_add_u32 s0, s0, 0x2000
	s_addc_u32 s1, s1, 0
	global_load_dword v33, v23, s[0:1] nt
	s_add_u32 s0, s0, 0x2000
	s_addc_u32 s1, s1, 0
	global_load_dword v34, v23, s[0:1] nt
	s_add_u32 s0, s0, 0x2000
	s_addc_u32 s1, s1, 0
	global_load_dword v35, v23, s[0:1] nt
	s_add_u32 s0, s0, 0x2000
	s_addc_u32 s1, s1, 0
	global_load_dword v36, v23, s[0:1] nt
	s_add_u32 s0, s0, 0x2000
	s_addc_u32 s1, s1, 0
	global_load_dword v37, v23, s[0:1] nt
	s_add_u32 s0, s0, 0x2000
	s_addc_u32 s1, s1, 0
	global_load_dword v38, v23, s[0:1] nt
	s_add_u32 s0, s0, 0x2000
	s_addc_u32 s1, s1, 0
	global_load_dword v39, v23, s[0:1] nt
	s_add_u32 s0, s0, 0x2000
	s_addc_u32 s1, s1, 0
	global_load_dword v40, v23, s[0:1] nt
	s_add_u32 s0, s0, 0x2000
	s_addc_u32 s1, s1, 0
	global_load_dword v41, v23, s[0:1] nt
	s_add_u32 s0, s0, 0x2000
	s_addc_u32 s1, s1, 0
	global_load_dword v42, v23, s[0:1] nt
	s_add_u32 s0, s0, 0x2000
	s_addc_u32 s1, s1, 0
	global_load_dword v43, v23, s[0:1] nt
	s_add_u32 s0, s0, 0x2000
	s_addc_u32 s1, s1, 0
	global_load_dword v44, v23, s[0:1] nt
	s_add_u32 s0, s0, 0x2000
	s_addc_u32 s1, s1, 0
	global_load_dword v45, v23, s[0:1] nt
	s_add_u32 s0, s0, 0x2000
	s_addc_u32 s1, s1, 0
	global_load_dword v46, v23, s[0:1] nt
	s_add_u32 s0, s0, 0x2000
	s_addc_u32 s1, s1, 0
	global_load_dword v47, v23, s[0:1] nt
	s_add_u32 s0, s0, 0x2000
	s_addc_u32 s1, s1, 0
	global_load_dword v48, v23, s[0:1] nt
	s_add_u32 s0, s0, 0x2000
	s_addc_u32 s1, s1, 0
	global_load_dword v49, v23, s[0:1] nt
	s_add_u32 s0, s0, 0x2000
	s_addc_u32 s1, s1, 0
	global_load_dword v50, v23, s[0:1] nt
	s_add_u32 s0, s0, 0x2000
	s_addc_u32 s1, s1, 0
	global_load_dword v51, v23, s[0:1] nt
	s_add_u32 s0, s0, 0x2000
	s_addc_u32 s1, s1, 0
	global_load_dword v52, v23, s[0:1] nt
	s_add_u32 s0, s0, 0x2000
	s_addc_u32 s1, s1, 0
	global_load_dword v53, v23, s[0:1] nt
	s_add_u32 s0, s0, 0x2000
	s_addc_u32 s1, s1, 0
	global_load_dword v54, v23, s[0:1] nt
	s_add_u32 s0, s0, 0x2000
	s_addc_u32 s1, s1, 0
	global_load_dword v55, v23, s[0:1] nt
	s_add_u32 s0, s0, 0x2000
	s_addc_u32 s1, s1, 0
	global_load_dword v56, v23, s[0:1] nt
	s_add_u32 s0, s0, 0x2000
	s_addc_u32 s1, s1, 0
	global_load_dword v57, v23, s[0:1] nt
	s_add_u32 s0, s0, 0x2000
	s_addc_u32 s1, s1, 0
	global_load_dword v58, v23, s[0:1] nt
	s_add_u32 s0, s0, 0x2000
	s_addc_u32 s1, s1, 0
	global_load_dword v59, v23, s[0:1] nt
	s_add_u32 s0, s0, 0x2000
	s_addc_u32 s1, s1, 0
	global_load_dword v60, v23, s[0:1] nt
	s_add_u32 s0, s0, 0x2000
	s_addc_u32 s1, s1, 0
	global_load_dword v61, v23, s[0:1] nt
	s_add_u32 s0, s0, 0x2000
	s_addc_u32 s1, s1, 0
	global_load_dword v62, v23, s[0:1] nt
	s_add_u32 s0, s0, 0x2000
	s_addc_u32 s1, s1, 0
	global_load_dword v63, v23, s[0:1] nt
	s_waitcnt vmcnt(31)
	ds_write_b32 v19, v32
	s_waitcnt vmcnt(30)
	ds_write_b32 v19, v33 offset:264
	s_waitcnt vmcnt(29)
	ds_write_b32 v19, v34 offset:528
	s_waitcnt vmcnt(28)
	ds_write_b32 v19, v35 offset:792
	s_waitcnt vmcnt(27)
	ds_write_b32 v19, v36 offset:1056
	s_waitcnt vmcnt(26)
	ds_write_b32 v19, v37 offset:1320
	s_waitcnt vmcnt(25)
	ds_write_b32 v19, v38 offset:1584
	s_waitcnt vmcnt(24)
	ds_write_b32 v19, v39 offset:1848
	s_waitcnt vmcnt(23)
; #define LAS __attribute__((address_space(3)))
; __device__ __forceinline__ unsigned cvt_pk_bf16(float lo, float hi) { unsigned r; asm volatile("v_cvt_pk_bf16_f32 %0, %1, %2" : "=v"(r) : "v"(lo), "v"(hi)); return r; }
; #define ST16(grp, p, v) do { if ((NTG >> (grp)) & 1) NT16(p, v); else PL16(p, v); } while (0)
; __device__ __forceinline__ void transpose_item(const float* W, int K, int N, bf16_t* WT, int n0src, int n0dst, int k0, LAS float* scr, int lane) {
;     ...
;     for (int i = 0; i < 32; ++i) { const int kk = 2 * i + (lane >> 5); v[i] = W[(size_t)(k0 + kk) * N + n0src + (lane & 31)]; }
; #pragma unroll
;     for (int i = 0; i < 32; ++i) { const int kk = 2 * i + (lane >> 5); scr[kk * 33 + (lane & 31)] = v[i]; }
;     asm volatile("s_waitcnt lgkmcnt(0)" ::: "memory");
;     const int c = lane & 7;
; #pragma unroll
;     for (int j = 0; j < 4; ++j) { const int n = (lane >> 3) + 8 * j; const LAS float* s = scr + (8 * c) * 33 + n;
;         u32x4 o; o.x = cvt_pk_bf16(s[0 * 33], s[1 * 33]); o.y = cvt_pk_bf16(s[2 * 33], s[3 * 33]); o.z = cvt_pk_bf16(s[4 * 33], s[5 * 33]); o.w = cvt_pk_bf16(s[6 * 33], s[7 * 33]);
;         ST16(6, WT + (size_t)(n0dst + n) * K + k0 + 8 * c, o); }
;     asm volatile("s_waitcnt lgkmcnt(0)" ::: "memory");
; }
; __device__ __forceinline__ void prologue(const Params& p, LAS unsigned char* lds) {
;     ...
;             if (r < 4 * I_W1) { const int mi = r / I_W1; r -= mi * I_W1; const int kb = r / 176, nb = r % 176;
;                 transpose_item(p.in[I_FFNWIN] + (size_t)mi * D * NFF1, D, NFF1, (bf16_t*)(ws + WS_W1T + mi * SZ_W1T), paired_src(nb * 32, DFF), nb * 32, kb * 64, scr, lane); continue; }
	ds_write_b32 v19, v40 offset:2112
	s_waitcnt vmcnt(22)
	ds_write_b32 v19, v41 offset:2376
	s_waitcnt vmcnt(21)
	ds_write_b32 v19, v42 offset:2640
	s_waitcnt vmcnt(20)
	ds_write_b32 v19, v43 offset:2904
	s_waitcnt vmcnt(19)
	ds_write_b32 v19, v44 offset:3168
	s_waitcnt vmcnt(18)
	ds_write_b32 v19, v45 offset:3432
	s_waitcnt vmcnt(17)
	ds_write_b32 v19, v46 offset:3696
	s_waitcnt vmcnt(16)
	ds_write_b32 v19, v47 offset:3960
	s_waitcnt vmcnt(15)
	ds_write_b32 v19, v48 offset:4224
	s_waitcnt vmcnt(14)
	ds_write_b32 v19, v49 offset:4488
	s_waitcnt vmcnt(13)
	ds_write_b32 v19, v50 offset:4752
	s_waitcnt vmcnt(12)
	ds_write_b32 v19, v51 offset:5016
	s_waitcnt vmcnt(11)
	ds_write_b32 v19, v52 offset:5280
	s_waitcnt vmcnt(10)
	ds_write_b32 v19, v53 offset:5544
	s_waitcnt vmcnt(9)
	ds_write_b32 v19, v54 offset:5808
	s_waitcnt vmcnt(8)
	ds_write_b32 v19, v55 offset:6072
	s_waitcnt vmcnt(7)
	ds_write_b32 v19, v56 offset:6336
	s_waitcnt vmcnt(6)
	ds_write_b32 v19, v57 offset:6600
	s_waitcnt vmcnt(5)
	ds_write_b32 v19, v58 offset:6864
	s_waitcnt vmcnt(4)
	ds_write_b32 v19, v59 offset:7128
	s_waitcnt vmcnt(3)
	ds_write_b32 v19, v60 offset:7392
	s_waitcnt vmcnt(2)
	ds_write_b32 v19, v61 offset:7656
	s_waitcnt vmcnt(1)
	ds_write_b32 v19, v62 offset:7920
	s_waitcnt vmcnt(0)
	ds_write_b32 v19, v63 offset:8184
	s_mul_i32 s0, s101, 0x2c000
	s_lshl_b32 s1, s100, 7
	s_add_u32 s0, s0, s1
	s_add_u32 s0, s34, s0
	s_addc_u32 s1, s35, 0
	s_waitcnt lgkmcnt(0)
	ds_read_b32 v64, v22
	ds_read_b32 v65, v22 offset:132
	ds_read_b32 v66, v22 offset:264
	ds_read_b32 v67, v22 offset:396
	ds_read_b32 v68, v22 offset:528
	ds_read_b32 v69, v22 offset:660
	ds_read_b32 v70, v22 offset:792
	ds_read_b32 v71, v22 offset:924
	ds_read_b32 v72, v22 offset:32
	ds_read_b32 v73, v22 offset:164
	ds_read_b32 v74, v22 offset:296
	ds_read_b32 v75, v22 offset:428
	ds_read_b32 v76, v22 offset:560
	ds_read_b32 v77, v22 offset:692
	ds_read_b32 v78, v22 offset:824
	ds_read_b32 v79, v22 offset:956
	ds_read_b32 v80, v22 offset:64
	ds_read_b32 v81, v22 offset:196
	ds_read_b32 v82, v22 offset:328
	ds_read_b32 v83, v22 offset:460
	ds_read_b32 v84, v22 offset:592
	ds_read_b32 v85, v22 offset:724
	ds_read_b32 v86, v22 offset:856
	ds_read_b32 v87, v22 offset:988
	ds_read_b32 v88, v22 offset:96
	ds_read_b32 v89, v22 offset:228
	ds_read_b32 v90, v22 offset:360
	ds_read_b32 v91, v22 offset:492
	ds_read_b32 v92, v22 offset:624
	ds_read_b32 v93, v22 offset:756
	ds_read_b32 v94, v22 offset:888
	ds_read_b32 v95, v22 offset:1020
	s_waitcnt lgkmcnt(15)
	v_cvt_pk_bf16_f32 v96, v64, v65
	v_cvt_pk_bf16_f32 v97, v66, v67
	v_cvt_pk_bf16_f32 v98, v68, v69
	v_cvt_pk_bf16_f32 v99, v70, v71
	global_store_dwordx4 v24, v[96:99], s[0:1]
	s_add_u32 s0, s0, 0xb000
	s_addc_u32 s1, s1, 0
	s_waitcnt lgkmcnt(15)
	v_cvt_pk_bf16_f32 v100, v72, v73
	v_cvt_pk_bf16_f32 v101, v74, v75
	v_cvt_pk_bf16_f32 v102, v76, v77
	v_cvt_pk_bf16_f32 v103, v78, v79
	global_store_dwordx4 v24, v[100:103], s[0:1]
	s_add_u32 s0, s0, 0xb000
	s_addc_u32 s1, s1, 0
	s_waitcnt lgkmcnt(8)
	v_cvt_pk_bf16_f32 v104, v80, v81
	v_cvt_pk_bf16_f32 v105, v82, v83
	v_cvt_pk_bf16_f32 v106, v84, v85
	v_cvt_pk_bf16_f32 v107, v86, v87
	global_store_dwordx4 v24, v[104:107], s[0:1]
	s_add_u32 s0, s0, 0xb000
	s_addc_u32 s1, s1, 0
	s_waitcnt lgkmcnt(0)
	v_cvt_pk_bf16_f32 v108, v88, v89
	v_cvt_pk_bf16_f32 v109, v90, v91
	v_cvt_pk_bf16_f32 v110, v92, v93
	v_cvt_pk_bf16_f32 v111, v94, v95
	global_store_dwordx4 v24, v[108:111], s[0:1]
.Ltr_end_a0:
	v_mul_u32_u24_e32 v23, 0x5800, v18
	v_lshl_add_u32 v23, v17, 2, v23
	v_lshlrev_b32_e32 v24, 11, v21
	v_lshl_add_u32 v24, v20, 4, v24
	v_mov_b32_e32 v25, 0x23f00
	ds_read_b64 v[26:27], v25
	s_waitcnt lgkmcnt(0)
	v_readfirstlane_b32 s32, v26
	v_readfirstlane_b32 s33, v27
	s_add_u32 s32, s32, 0x4200000
	s_addc_u32 s33, s33, 0
	s_add_u32 s34, s76, 0x2300000
	s_addc_u32 s35, s77, 0
	s_mov_b32 s98, s36
	s_cmpk_ge_u32 s98, 0xb00
	s_cbranch_scc1 .Ltr_end_a1
.Ltr_loop_a1:
	s_add_i32 s40, s98, 0x400
	s_cmpk_ge_u32 s40, 0xb00
	s_cbranch_scc1 .Ltr_single_a1
	s_and_b32 s100, s98, 15
	s_lshr_b32 s101, s98, 4
	s_lshr_b32 s0, s101, 3
	s_lshl_b32 s0, s0, 7
	s_and_b32 s1, s101, 7
	s_lshl_b32 s1, s1, 5
	s_add_u32 s0, s0, s1
	s_add_u32 s1, s0, 0xa80
	s_bitcmp1_b32 s101, 2
	s_cselect_b32 s0, s1, s0
	s_lshl_b32 s0, s0, 2
	s_mul_i32 s1, s100, 0x160000
	s_add_u32 s0, s0, s1
	s_add_u32 s0, s32, s0
	s_addc_u32 s1, s33, 0
	global_load_dword v32, v23, s[0:1] nt
	s_add_u32 s0, s0, 0xb000
	s_addc_u32 s1, s1, 0
	global_load_dword v33, v23, s[0:1] nt
	s_add_u32 s0, s0, 0xb000
	s_addc_u32 s1, s1, 0
	global_load_dword v34, v23, s[0:1] nt
	s_add_u32 s0, s0, 0xb000
	s_addc_u32 s1, s1, 0
	global_load_dword v35, v23, s[0:1] nt
	s_add_u32 s0, s0, 0xb000
	s_addc_u32 s1, s1, 0
	global_load_dword v36, v23, s[0:1] nt
	s_add_u32 s0, s0, 0xb000
	s_addc_u32 s1, s1, 0
	global_load_dword v37, v23, s[0:1] nt
	s_add_u32 s0, s0, 0xb000
	s_addc_u32 s1, s1, 0
	global_load_dword v38, v23, s[0:1] nt
	s_add_u32 s0, s0, 0xb000
	s_addc_u32 s1, s1, 0
	global_load_dword v39, v23, s[0:1] nt
	s_add_u32 s0, s0, 0xb000
	s_addc_u32 s1, s1, 0
	global_load_dword v40, v23, s[0:1] nt
	s_add_u32 s0, s0, 0xb000
	s_addc_u32 s1, s1, 0
	global_load_dword v41, v23, s[0:1] nt
	s_add_u32 s0, s0, 0xb000
	s_addc_u32 s1, s1, 0
	global_load_dword v42, v23, s[0:1] nt
	s_add_u32 s0, s0, 0xb000
	s_addc_u32 s1, s1, 0
	global_load_dword v43, v23, s[0:1] nt
	s_add_u32 s0, s0, 0xb000
	s_addc_u32 s1, s1, 0
	global_load_dword v44, v23, s[0:1] nt
	s_add_u32 s0, s0, 0xb000
	s_addc_u32 s1, s1, 0
	global_load_dword v45, v23, s[0:1] nt
	s_add_u32 s0, s0, 0xb000
	s_addc_u32 s1, s1, 0
	global_load_dword v46, v23, s[0:1] nt
; #define LAS __attribute__((address_space(3)))
; __device__ __forceinline__ void transpose_item(const float* W, int K, int N, bf16_t* WT, int n0src, int n0dst, int k0, LAS float* scr, int lane) {
;     float v[32];
; #pragma unroll
;     for (int i = 0; i < 32; ++i) { const int kk = 2 * i + (lane >> 5); v[i] = W[(size_t)(k0 + kk) * N + n0src + (lane & 31)]; }
; #pragma unroll
;     for (int i = 0; i < 32; ++i) { const int kk = 2 * i + (lane >> 5); scr[kk * 33 + (lane & 31)] = v[i]; }
	s_add_u32 s0, s0, 0xb000
	s_addc_u32 s1, s1, 0
	global_load_dword v47, v23, s[0:1] nt
	s_add_u32 s0, s0, 0xb000
	s_addc_u32 s1, s1, 0
	global_load_dword v48, v23, s[0:1] nt
	s_add_u32 s0, s0, 0xb000
	s_addc_u32 s1, s1, 0
	global_load_dword v49, v23, s[0:1] nt
	s_add_u32 s0, s0, 0xb000
	s_addc_u32 s1, s1, 0
	global_load_dword v50, v23, s[0:1] nt
	s_add_u32 s0, s0, 0xb000
	s_addc_u32 s1, s1, 0
	global_load_dword v51, v23, s[0:1] nt
	s_add_u32 s0, s0, 0xb000
	s_addc_u32 s1, s1, 0
	global_load_dword v52, v23, s[0:1] nt
	s_add_u32 s0, s0, 0xb000
	s_addc_u32 s1, s1, 0
	global_load_dword v53, v23, s[0:1] nt
	s_add_u32 s0, s0, 0xb000
	s_addc_u32 s1, s1, 0
	global_load_dword v54, v23, s[0:1] nt
	s_add_u32 s0, s0, 0xb000
	s_addc_u32 s1, s1, 0
	global_load_dword v55, v23, s[0:1] nt
	s_add_u32 s0, s0, 0xb000
	s_addc_u32 s1, s1, 0
	global_load_dword v56, v23, s[0:1] nt
	s_add_u32 s0, s0, 0xb000
	s_addc_u32 s1, s1, 0
	global_load_dword v57, v23, s[0:1] nt
	s_add_u32 s0, s0, 0xb000
	s_addc_u32 s1, s1, 0
	global_load_dword v58, v23, s[0:1] nt
	s_add_u32 s0, s0, 0xb000
	s_addc_u32 s1, s1, 0
	global_load_dword v59, v23, s[0:1] nt
	s_add_u32 s0, s0, 0xb000
	s_addc_u32 s1, s1, 0
	global_load_dword v60, v23, s[0:1] nt
	s_add_u32 s0, s0, 0xb000
	s_addc_u32 s1, s1, 0
	global_load_dword v61, v23, s[0:1] nt
	s_add_u32 s0, s0, 0xb000
	s_addc_u32 s1, s1, 0
	global_load_dword v62, v23, s[0:1] nt
	s_add_u32 s0, s0, 0xb000
	s_addc_u32 s1, s1, 0
	global_load_dword v63, v23, s[0:1] nt
	s_and_b32 s41, s40, 15
	s_lshr_b32 s42, s40, 4
	s_lshr_b32 s0, s42, 3
	s_lshl_b32 s0, s0, 7
	s_and_b32 s1, s42, 7
	s_lshl_b32 s1, s1, 5
	s_add_u32 s0, s0, s1
	s_add_u32 s1, s0, 0xa80
	s_bitcmp1_b32 s42, 2
	s_cselect_b32 s0, s1, s0
	s_lshl_b32 s0, s0, 2
	s_mul_i32 s1, s41, 0x160000
	s_add_u32 s0, s0, s1
	s_add_u32 s0, s32, s0
	s_addc_u32 s1, s33, 0
	global_load_dword v112, v23, s[0:1] nt
	s_add_u32 s0, s0, 0xb000
	s_addc_u32 s1, s1, 0
	global_load_dword v113, v23, s[0:1] nt
	s_add_u32 s0, s0, 0xb000
	s_addc_u32 s1, s1, 0
	global_load_dword v114, v23, s[0:1] nt
	s_add_u32 s0, s0, 0xb000
	s_addc_u32 s1, s1, 0
	global_load_dword v115, v23, s[0:1] nt
	s_add_u32 s0, s0, 0xb000
	s_addc_u32 s1, s1, 0
	global_load_dword v116, v23, s[0:1] nt
	s_add_u32 s0, s0, 0xb000
	s_addc_u32 s1, s1, 0
	global_load_dword v117, v23, s[0:1] nt
	s_add_u32 s0, s0, 0xb000
	s_addc_u32 s1, s1, 0
	global_load_dword v118, v23, s[0:1] nt
	s_add_u32 s0, s0, 0xb000
	s_addc_u32 s1, s1, 0
	global_load_dword v119, v23, s[0:1] nt
	s_add_u32 s0, s0, 0xb000
	s_addc_u32 s1, s1, 0
	global_load_dword v120, v23, s[0:1] nt
	s_add_u32 s0, s0, 0xb000
	s_addc_u32 s1, s1, 0
	global_load_dword v121, v23, s[0:1] nt
	s_add_u32 s0, s0, 0xb000
	s_addc_u32 s1, s1, 0
	global_load_dword v122, v23, s[0:1] nt
	s_add_u32 s0, s0, 0xb000
	s_addc_u32 s1, s1, 0
	global_load_dword v123, v23, s[0:1] nt
	s_add_u32 s0, s0, 0xb000
	s_addc_u32 s1, s1, 0
	global_load_dword v124, v23, s[0:1] nt
	s_add_u32 s0, s0, 0xb000
	s_addc_u32 s1, s1, 0
	global_load_dword v125, v23, s[0:1] nt
	s_add_u32 s0, s0, 0xb000
	s_addc_u32 s1, s1, 0
	global_load_dword v126, v23, s[0:1] nt
	s_add_u32 s0, s0, 0xb000
	s_addc_u32 s1, s1, 0
	global_load_dword v127, v23, s[0:1] nt
	s_add_u32 s0, s0, 0xb000
	s_addc_u32 s1, s1, 0
	global_load_dword v128, v23, s[0:1] nt
	s_add_u32 s0, s0, 0xb000
	s_addc_u32 s1, s1, 0
	global_load_dword v129, v23, s[0:1] nt
	s_add_u32 s0, s0, 0xb000
	s_addc_u32 s1, s1, 0
	global_load_dword v130, v23, s[0:1] nt
	s_add_u32 s0, s0, 0xb000
	s_addc_u32 s1, s1, 0
	global_load_dword v131, v23, s[0:1] nt
	s_add_u32 s0, s0, 0xb000
	s_addc_u32 s1, s1, 0
	global_load_dword v132, v23, s[0:1] nt
	s_add_u32 s0, s0, 0xb000
	s_addc_u32 s1, s1, 0
	global_load_dword v133, v23, s[0:1] nt
	s_add_u32 s0, s0, 0xb000
	s_addc_u32 s1, s1, 0
	global_load_dword v134, v23, s[0:1] nt
	s_add_u32 s0, s0, 0xb000
	s_addc_u32 s1, s1, 0
	global_load_dword v135, v23, s[0:1] nt
	s_add_u32 s0, s0, 0xb000
	s_addc_u32 s1, s1, 0
	global_load_dword v136, v23, s[0:1] nt
	s_add_u32 s0, s0, 0xb000
	s_addc_u32 s1, s1, 0
	global_load_dword v137, v23, s[0:1] nt
	s_add_u32 s0, s0, 0xb000
	s_addc_u32 s1, s1, 0
	global_load_dword v138, v23, s[0:1] nt
	s_add_u32 s0, s0, 0xb000
	s_addc_u32 s1, s1, 0
	global_load_dword v139, v23, s[0:1] nt
	s_add_u32 s0, s0, 0xb000
	s_addc_u32 s1, s1, 0
	global_load_dword v140, v23, s[0:1] nt
	s_add_u32 s0, s0, 0xb000
	s_addc_u32 s1, s1, 0
	global_load_dword v141, v23, s[0:1] nt
	s_add_u32 s0, s0, 0xb000
	s_addc_u32 s1, s1, 0
	global_load_dword v142, v23, s[0:1] nt
	s_add_u32 s0, s0, 0xb000
	s_addc_u32 s1, s1, 0
	global_load_dword v143, v23, s[0:1] nt
	s_waitcnt vmcnt(63)
	ds_write_b32 v19, v32
	s_waitcnt vmcnt(62)
	ds_write_b32 v19, v33 offset:264
	s_waitcnt vmcnt(61)
	ds_write_b32 v19, v34 offset:528
	s_waitcnt vmcnt(60)
	ds_write_b32 v19, v35 offset:792
	s_waitcnt vmcnt(59)
	ds_write_b32 v19, v36 offset:1056
	s_waitcnt vmcnt(58)
	ds_write_b32 v19, v37 offset:1320
	s_waitcnt vmcnt(57)
	ds_write_b32 v19, v38 offset:1584
	s_waitcnt vmcnt(56)
	ds_write_b32 v19, v39 offset:1848
	s_waitcnt vmcnt(55)
	ds_write_b32 v19, v40 offset:2112
	s_waitcnt vmcnt(54)
	ds_write_b32 v19, v41 offset:2376
	s_waitcnt vmcnt(53)
	ds_write_b32 v19, v42 offset:2640
	s_waitcnt vmcnt(52)
	ds_write_b32 v19, v43 offset:2904
	s_waitcnt vmcnt(51)
	ds_write_b32 v19, v44 offset:3168
	s_waitcnt vmcnt(50)
	ds_write_b32 v19, v45 offset:3432
	s_waitcnt vmcnt(49)
	ds_write_b32 v19, v46 offset:3696
	s_waitcnt vmcnt(48)
	ds_write_b32 v19, v47 offset:3960
	s_waitcnt vmcnt(47)
	ds_write_b32 v19, v48 offset:4224
	s_waitcnt vmcnt(46)
	ds_write_b32 v19, v49 offset:4488
	s_waitcnt vmcnt(45)
; #define LAS __attribute__((address_space(3)))
; __device__ __forceinline__ unsigned cvt_pk_bf16(float lo, float hi) { unsigned r; asm volatile("v_cvt_pk_bf16_f32 %0, %1, %2" : "=v"(r) : "v"(lo), "v"(hi)); return r; }
; #define ST16(grp, p, v) do { if ((NTG >> (grp)) & 1) NT16(p, v); else PL16(p, v); } while (0)
; __device__ __forceinline__ void transpose_item(const float* W, int K, int N, bf16_t* WT, int n0src, int n0dst, int k0, LAS float* scr, int lane) {
;     ...
;     for (int i = 0; i < 32; ++i) { const int kk = 2 * i + (lane >> 5); v[i] = W[(size_t)(k0 + kk) * N + n0src + (lane & 31)]; }
; #pragma unroll
;     for (int i = 0; i < 32; ++i) { const int kk = 2 * i + (lane >> 5); scr[kk * 33 + (lane & 31)] = v[i]; }
;     asm volatile("s_waitcnt lgkmcnt(0)" ::: "memory");
;     const int c = lane & 7;
; #pragma unroll
;     for (int j = 0; j < 4; ++j) { const int n = (lane >> 3) + 8 * j; const LAS float* s = scr + (8 * c) * 33 + n;
;         u32x4 o; o.x = cvt_pk_bf16(s[0 * 33], s[1 * 33]); o.y = cvt_pk_bf16(s[2 * 33], s[3 * 33]); o.z = cvt_pk_bf16(s[4 * 33], s[5 * 33]); o.w = cvt_pk_bf16(s[6 * 33], s[7 * 33]);
;         ST16(6, WT + (size_t)(n0dst + n) * K + k0 + 8 * c, o); }
;     asm volatile("s_waitcnt lgkmcnt(0)" ::: "memory");
; }
	ds_write_b32 v19, v50 offset:4752
	s_waitcnt vmcnt(44)
	ds_write_b32 v19, v51 offset:5016
	s_waitcnt vmcnt(43)
	ds_write_b32 v19, v52 offset:5280
	s_waitcnt vmcnt(42)
	ds_write_b32 v19, v53 offset:5544
	s_waitcnt vmcnt(41)
	ds_write_b32 v19, v54 offset:5808
	s_waitcnt vmcnt(40)
	ds_write_b32 v19, v55 offset:6072
	s_waitcnt vmcnt(39)
	ds_write_b32 v19, v56 offset:6336
	s_waitcnt vmcnt(38)
	ds_write_b32 v19, v57 offset:6600
	s_waitcnt vmcnt(37)
	ds_write_b32 v19, v58 offset:6864
	s_waitcnt vmcnt(36)
	ds_write_b32 v19, v59 offset:7128
	s_waitcnt vmcnt(35)
	ds_write_b32 v19, v60 offset:7392
	s_waitcnt vmcnt(34)
	ds_write_b32 v19, v61 offset:7656
	s_waitcnt vmcnt(33)
	ds_write_b32 v19, v62 offset:7920
	s_waitcnt vmcnt(32)
	ds_write_b32 v19, v63 offset:8184
	s_lshl_b32 s0, s101, 16
	s_lshl_b32 s1, s100, 7
	s_add_u32 s0, s0, s1
	s_add_u32 s0, s34, s0
	s_addc_u32 s1, s35, 0
	s_waitcnt lgkmcnt(0)
	ds_read_b32 v64, v22
	ds_read_b32 v65, v22 offset:132
	ds_read_b32 v66, v22 offset:264
	ds_read_b32 v67, v22 offset:396
	ds_read_b32 v68, v22 offset:528
	ds_read_b32 v69, v22 offset:660
	ds_read_b32 v70, v22 offset:792
	ds_read_b32 v71, v22 offset:924
	ds_read_b32 v72, v22 offset:32
	ds_read_b32 v73, v22 offset:164
	ds_read_b32 v74, v22 offset:296
	ds_read_b32 v75, v22 offset:428
	ds_read_b32 v76, v22 offset:560
	ds_read_b32 v77, v22 offset:692
	ds_read_b32 v78, v22 offset:824
	ds_read_b32 v79, v22 offset:956
	ds_read_b32 v80, v22 offset:64
	ds_read_b32 v81, v22 offset:196
	ds_read_b32 v82, v22 offset:328
	ds_read_b32 v83, v22 offset:460
	ds_read_b32 v84, v22 offset:592
	ds_read_b32 v85, v22 offset:724
	ds_read_b32 v86, v22 offset:856
	ds_read_b32 v87, v22 offset:988
	ds_read_b32 v88, v22 offset:96
	ds_read_b32 v89, v22 offset:228
	ds_read_b32 v90, v22 offset:360
	ds_read_b32 v91, v22 offset:492
	ds_read_b32 v92, v22 offset:624
	ds_read_b32 v93, v22 offset:756
	ds_read_b32 v94, v22 offset:888
	ds_read_b32 v95, v22 offset:1020
	s_waitcnt lgkmcnt(15)
	v_cvt_pk_bf16_f32 v96, v64, v65
	v_cvt_pk_bf16_f32 v97, v66, v67
	v_cvt_pk_bf16_f32 v98, v68, v69
	v_cvt_pk_bf16_f32 v99, v70, v71
	global_store_dwordx4 v24, v[96:99], s[0:1]
	s_add_u32 s0, s0, 0x4000
	s_addc_u32 s1, s1, 0
	s_waitcnt lgkmcnt(15)
	v_cvt_pk_bf16_f32 v100, v72, v73
	v_cvt_pk_bf16_f32 v101, v74, v75
	v_cvt_pk_bf16_f32 v102, v76, v77
	v_cvt_pk_bf16_f32 v103, v78, v79
	global_store_dwordx4 v24, v[100:103], s[0:1]
	s_add_u32 s0, s0, 0x4000
	s_addc_u32 s1, s1, 0
	s_waitcnt lgkmcnt(8)
	v_cvt_pk_bf16_f32 v104, v80, v81
	v_cvt_pk_bf16_f32 v105, v82, v83
	v_cvt_pk_bf16_f32 v106, v84, v85
	v_cvt_pk_bf16_f32 v107, v86, v87
	global_store_dwordx4 v24, v[104:107], s[0:1]
	s_add_u32 s0, s0, 0x4000
	s_addc_u32 s1, s1, 0
	s_waitcnt lgkmcnt(0)
	v_cvt_pk_bf16_f32 v108, v88, v89
	v_cvt_pk_bf16_f32 v109, v90, v91
	v_cvt_pk_bf16_f32 v110, v92, v93
	v_cvt_pk_bf16_f32 v111, v94, v95
	global_store_dwordx4 v24, v[108:111], s[0:1]
	s_waitcnt vmcnt(31)
	ds_write_b32 v19, v112
	s_waitcnt vmcnt(30)
	ds_write_b32 v19, v113 offset:264
	s_waitcnt vmcnt(29)
	ds_write_b32 v19, v114 offset:528
	s_waitcnt vmcnt(28)
	ds_write_b32 v19, v115 offset:792
	s_waitcnt vmcnt(27)
	ds_write_b32 v19, v116 offset:1056
	s_waitcnt vmcnt(26)
	ds_write_b32 v19, v117 offset:1320
	s_waitcnt vmcnt(25)
	ds_write_b32 v19, v118 offset:1584
	s_waitcnt vmcnt(24)
	ds_write_b32 v19, v119 offset:1848
	s_waitcnt vmcnt(23)
	ds_write_b32 v19, v120 offset:2112
	s_waitcnt vmcnt(22)
	ds_write_b32 v19, v121 offset:2376
	s_waitcnt vmcnt(21)
	ds_write_b32 v19, v122 offset:2640
	s_waitcnt vmcnt(20)
	ds_write_b32 v19, v123 offset:2904
	s_waitcnt vmcnt(19)
	ds_write_b32 v19, v124 offset:3168
	s_waitcnt vmcnt(18)
	ds_write_b32 v19, v125 offset:3432
	s_waitcnt vmcnt(17)
	ds_write_b32 v19, v126 offset:3696
	s_waitcnt vmcnt(16)
	ds_write_b32 v19, v127 offset:3960
	s_waitcnt vmcnt(15)
	ds_write_b32 v19, v128 offset:4224
	s_waitcnt vmcnt(14)
	ds_write_b32 v19, v129 offset:4488
	s_waitcnt vmcnt(13)
	ds_write_b32 v19, v130 offset:4752
	s_waitcnt vmcnt(12)
	ds_write_b32 v19, v131 offset:5016
	s_waitcnt vmcnt(11)
	ds_write_b32 v19, v132 offset:5280
	s_waitcnt vmcnt(10)
	ds_write_b32 v19, v133 offset:5544
	s_waitcnt vmcnt(9)
	ds_write_b32 v19, v134 offset:5808
	s_waitcnt vmcnt(8)
	ds_write_b32 v19, v135 offset:6072
	s_waitcnt vmcnt(7)
	ds_write_b32 v19, v136 offset:6336
	s_waitcnt vmcnt(6)
	ds_write_b32 v19, v137 offset:6600
	s_waitcnt vmcnt(5)
	ds_write_b32 v19, v138 offset:6864
	s_waitcnt vmcnt(4)
	ds_write_b32 v19, v139 offset:7128
	s_waitcnt vmcnt(3)
	ds_write_b32 v19, v140 offset:7392
	s_waitcnt vmcnt(2)
	ds_write_b32 v19, v141 offset:7656
	s_waitcnt vmcnt(1)
	ds_write_b32 v19, v142 offset:7920
	s_waitcnt vmcnt(0)
	ds_write_b32 v19, v143 offset:8184
	s_lshl_b32 s0, s42, 16
	s_lshl_b32 s1, s41, 7
	s_add_u32 s0, s0, s1
	s_add_u32 s0, s34, s0
	s_addc_u32 s1, s35, 0
	s_waitcnt lgkmcnt(0)
	ds_read_b32 v64, v22
	ds_read_b32 v65, v22 offset:132
	ds_read_b32 v66, v22 offset:264
	ds_read_b32 v67, v22 offset:396
	ds_read_b32 v68, v22 offset:528
	ds_read_b32 v69, v22 offset:660
	ds_read_b32 v70, v22 offset:792
	ds_read_b32 v71, v22 offset:924
	ds_read_b32 v72, v22 offset:32
	ds_read_b32 v73, v22 offset:164
	ds_read_b32 v74, v22 offset:296
	ds_read_b32 v75, v22 offset:428
	ds_read_b32 v76, v22 offset:560
	ds_read_b32 v77, v22 offset:692
	ds_read_b32 v78, v22 offset:824
	ds_read_b32 v79, v22 offset:956
	ds_read_b32 v80, v22 offset:64
	ds_read_b32 v81, v22 offset:196
	ds_read_b32 v82, v22 offset:328
	ds_read_b32 v83, v22 offset:460
	ds_read_b32 v84, v22 offset:592
	ds_read_b32 v85, v22 offset:724
	ds_read_b32 v86, v22 offset:856
	ds_read_b32 v87, v22 offset:988
	ds_read_b32 v88, v22 offset:96
	ds_read_b32 v89, v22 offset:228
	ds_read_b32 v90, v22 offset:360
	ds_read_b32 v91, v22 offset:492
	ds_read_b32 v92, v22 offset:624
	ds_read_b32 v93, v22 offset:756
	ds_read_b32 v94, v22 offset:888
	ds_read_b32 v95, v22 offset:1020
	s_waitcnt lgkmcnt(15)
	v_cvt_pk_bf16_f32 v96, v64, v65
	v_cvt_pk_bf16_f32 v97, v66, v67
	v_cvt_pk_bf16_f32 v98, v68, v69
	v_cvt_pk_bf16_f32 v99, v70, v71
	global_store_dwordx4 v24, v[96:99], s[0:1]
	s_add_u32 s0, s0, 0x4000
	s_addc_u32 s1, s1, 0
	s_waitcnt lgkmcnt(15)
	v_cvt_pk_bf16_f32 v100, v72, v73
	v_cvt_pk_bf16_f32 v101, v74, v75
	v_cvt_pk_bf16_f32 v102, v76, v77
	v_cvt_pk_bf16_f32 v103, v78, v79
	global_store_dwordx4 v24, v[100:103], s[0:1]
	s_add_u32 s0, s0, 0x4000
	s_addc_u32 s1, s1, 0
	s_waitcnt lgkmcnt(8)
	v_cvt_pk_bf16_f32 v104, v80, v81
	v_cvt_pk_bf16_f32 v105, v82, v83
	v_cvt_pk_bf16_f32 v106, v84, v85
	v_cvt_pk_bf16_f32 v107, v86, v87
	global_store_dwordx4 v24, v[104:107], s[0:1]
	s_add_u32 s0, s0, 0x4000
	s_addc_u32 s1, s1, 0
	s_waitcnt lgkmcnt(0)
	v_cvt_pk_bf16_f32 v108, v88, v89
	v_cvt_pk_bf16_f32 v109, v90, v91
	v_cvt_pk_bf16_f32 v110, v92, v93
	v_cvt_pk_bf16_f32 v111, v94, v95
	global_store_dwordx4 v24, v[108:111], s[0:1]
	s_add_i32 s98, s98, 0x800
	s_cmpk_lt_u32 s98, 0xb00
	s_cbranch_scc1 .Ltr_loop_a1
	s_branch .Ltr_end_a1
; #define LAS __attribute__((address_space(3)))
; __device__ __forceinline__ unsigned cvt_pk_bf16(float lo, float hi) { unsigned r; asm volatile("v_cvt_pk_bf16_f32 %0, %1, %2" : "=v"(r) : "v"(lo), "v"(hi)); return r; }
; #define ST16(grp, p, v) do { if ((NTG >> (grp)) & 1) NT16(p, v); else PL16(p, v); } while (0)
; __device__ __forceinline__ void transpose_item(const float* W, int K, int N, bf16_t* WT, int n0src, int n0dst, int k0, LAS float* scr, int lane) {
;     float v[32];
; #pragma unroll
;     for (int i = 0; i < 32; ++i) { const int kk = 2 * i + (lane >> 5); v[i] = W[(size_t)(k0 + kk) * N + n0src + (lane & 31)]; }
; #pragma unroll
;     for (int i = 0; i < 32; ++i) { const int kk = 2 * i + (lane >> 5); scr[kk * 33 + (lane & 31)] = v[i]; }
;     asm volatile("s_waitcnt lgkmcnt(0)" ::: "memory");
;     const int c = lane & 7;
; #pragma unroll
;     for (int j = 0; j < 4; ++j) { const int n = (lane >> 3) + 8 * j; const LAS float* s = scr + (8 * c) * 33 + n;
;         u32x4 o; o.x = cvt_pk_bf16(s[0 * 33], s[1 * 33]); o.y = cvt_pk_bf16(s[2 * 33], s[3 * 33]); o.z = cvt_pk_bf16(s[4 * 33], s[5 * 33]); o.w = cvt_pk_bf16(s[6 * 33], s[7 * 33]);
;         ST16(6, WT + (size_t)(n0dst + n) * K + k0 + 8 * c, o); }
;     asm volatile("s_waitcnt lgkmcnt(0)" ::: "memory");
; }
.Ltr_single_a1:
	s_and_b32 s100, s98, 15
	s_lshr_b32 s101, s98, 4
	s_lshr_b32 s0, s101, 3
	s_lshl_b32 s0, s0, 7
	s_and_b32 s1, s101, 7
	s_lshl_b32 s1, s1, 5
	s_add_u32 s0, s0, s1
	s_add_u32 s1, s0, 0xa80
	s_bitcmp1_b32 s101, 2
	s_cselect_b32 s0, s1, s0
	s_lshl_b32 s0, s0, 2
	s_mul_i32 s1, s100, 0x160000
	s_add_u32 s0, s0, s1
	s_add_u32 s0, s32, s0
	s_addc_u32 s1, s33, 0
	global_load_dword v32, v23, s[0:1] nt
	s_add_u32 s0, s0, 0xb000
	s_addc_u32 s1, s1, 0
	global_load_dword v33, v23, s[0:1] nt
	s_add_u32 s0, s0, 0xb000
	s_addc_u32 s1, s1, 0
	global_load_dword v34, v23, s[0:1] nt
	s_add_u32 s0, s0, 0xb000
	s_addc_u32 s1, s1, 0
	global_load_dword v35, v23, s[0:1] nt
	s_add_u32 s0, s0, 0xb000
	s_addc_u32 s1, s1, 0
	global_load_dword v36, v23, s[0:1] nt
	s_add_u32 s0, s0, 0xb000
	s_addc_u32 s1, s1, 0
	global_load_dword v37, v23, s[0:1] nt
	s_add_u32 s0, s0, 0xb000
	s_addc_u32 s1, s1, 0
	global_load_dword v38, v23, s[0:1] nt
	s_add_u32 s0, s0, 0xb000
	s_addc_u32 s1, s1, 0
	global_load_dword v39, v23, s[0:1] nt
	s_add_u32 s0, s0, 0xb000
	s_addc_u32 s1, s1, 0
	global_load_dword v40, v23, s[0:1] nt
	s_add_u32 s0, s0, 0xb000
	s_addc_u32 s1, s1, 0
	global_load_dword v41, v23, s[0:1] nt
	s_add_u32 s0, s0, 0xb000
	s_addc_u32 s1, s1, 0
	global_load_dword v42, v23, s[0:1] nt
	s_add_u32 s0, s0, 0xb000
	s_addc_u32 s1, s1, 0
	global_load_dword v43, v23, s[0:1] nt
	s_add_u32 s0, s0, 0xb000
	s_addc_u32 s1, s1, 0
	global_load_dword v44, v23, s[0:1] nt
	s_add_u32 s0, s0, 0xb000
	s_addc_u32 s1, s1, 0
	global_load_dword v45, v23, s[0:1] nt
	s_add_u32 s0, s0, 0xb000
	s_addc_u32 s1, s1, 0
	global_load_dword v46, v23, s[0:1] nt
	s_add_u32 s0, s0, 0xb000
	s_addc_u32 s1, s1, 0
	global_load_dword v47, v23, s[0:1] nt
	s_add_u32 s0, s0, 0xb000
	s_addc_u32 s1, s1, 0
	global_load_dword v48, v23, s[0:1] nt
	s_add_u32 s0, s0, 0xb000
	s_addc_u32 s1, s1, 0
	global_load_dword v49, v23, s[0:1] nt
	s_add_u32 s0, s0, 0xb000
	s_addc_u32 s1, s1, 0
	global_load_dword v50, v23, s[0:1] nt
	s_add_u32 s0, s0, 0xb000
	s_addc_u32 s1, s1, 0
	global_load_dword v51, v23, s[0:1] nt
	s_add_u32 s0, s0, 0xb000
	s_addc_u32 s1, s1, 0
	global_load_dword v52, v23, s[0:1] nt
	s_add_u32 s0, s0, 0xb000
	s_addc_u32 s1, s1, 0
	global_load_dword v53, v23, s[0:1] nt
	s_add_u32 s0, s0, 0xb000
	s_addc_u32 s1, s1, 0
	global_load_dword v54, v23, s[0:1] nt
	s_add_u32 s0, s0, 0xb000
	s_addc_u32 s1, s1, 0
	global_load_dword v55, v23, s[0:1] nt
	s_add_u32 s0, s0, 0xb000
	s_addc_u32 s1, s1, 0
	global_load_dword v56, v23, s[0:1] nt
	s_add_u32 s0, s0, 0xb000
	s_addc_u32 s1, s1, 0
	global_load_dword v57, v23, s[0:1] nt
	s_add_u32 s0, s0, 0xb000
	s_addc_u32 s1, s1, 0
	global_load_dword v58, v23, s[0:1] nt
	s_add_u32 s0, s0, 0xb000
	s_addc_u32 s1, s1, 0
	global_load_dword v59, v23, s[0:1] nt
	s_add_u32 s0, s0, 0xb000
	s_addc_u32 s1, s1, 0
	global_load_dword v60, v23, s[0:1] nt
	s_add_u32 s0, s0, 0xb000
	s_addc_u32 s1, s1, 0
	global_load_dword v61, v23, s[0:1] nt
	s_add_u32 s0, s0, 0xb000
	s_addc_u32 s1, s1, 0
	global_load_dword v62, v23, s[0:1] nt
	s_add_u32 s0, s0, 0xb000
	s_addc_u32 s1, s1, 0
	global_load_dword v63, v23, s[0:1] nt
	s_waitcnt vmcnt(31)
	ds_write_b32 v19, v32
	s_waitcnt vmcnt(30)
	ds_write_b32 v19, v33 offset:264
	s_waitcnt vmcnt(29)
	ds_write_b32 v19, v34 offset:528
	s_waitcnt vmcnt(28)
	ds_write_b32 v19, v35 offset:792
	s_waitcnt vmcnt(27)
	ds_write_b32 v19, v36 offset:1056
	s_waitcnt vmcnt(26)
	ds_write_b32 v19, v37 offset:1320
	s_waitcnt vmcnt(25)
	ds_write_b32 v19, v38 offset:1584
	s_waitcnt vmcnt(24)
	ds_write_b32 v19, v39 offset:1848
	s_waitcnt vmcnt(23)
	ds_write_b32 v19, v40 offset:2112
	s_waitcnt vmcnt(22)
	ds_write_b32 v19, v41 offset:2376
	s_waitcnt vmcnt(21)
	ds_write_b32 v19, v42 offset:2640
	s_waitcnt vmcnt(20)
	ds_write_b32 v19, v43 offset:2904
	s_waitcnt vmcnt(19)
	ds_write_b32 v19, v44 offset:3168
	s_waitcnt vmcnt(18)
	ds_write_b32 v19, v45 offset:3432
	s_waitcnt vmcnt(17)
	ds_write_b32 v19, v46 offset:3696
	s_waitcnt vmcnt(16)
	ds_write_b32 v19, v47 offset:3960
	s_waitcnt vmcnt(15)
	ds_write_b32 v19, v48 offset:4224
	s_waitcnt vmcnt(14)
	ds_write_b32 v19, v49 offset:4488
	s_waitcnt vmcnt(13)
	ds_write_b32 v19, v50 offset:4752
	s_waitcnt vmcnt(12)
	ds_write_b32 v19, v51 offset:5016
	s_waitcnt vmcnt(11)
	ds_write_b32 v19, v52 offset:5280
	s_waitcnt vmcnt(10)
	ds_write_b32 v19, v53 offset:5544
	s_waitcnt vmcnt(9)
	ds_write_b32 v19, v54 offset:5808
	s_waitcnt vmcnt(8)
	ds_write_b32 v19, v55 offset:6072
	s_waitcnt vmcnt(7)
	ds_write_b32 v19, v56 offset:6336
	s_waitcnt vmcnt(6)
	ds_write_b32 v19, v57 offset:6600
	s_waitcnt vmcnt(5)
	ds_write_b32 v19, v58 offset:6864
	s_waitcnt vmcnt(4)
	ds_write_b32 v19, v59 offset:7128
	s_waitcnt vmcnt(3)
	ds_write_b32 v19, v60 offset:7392
	s_waitcnt vmcnt(2)
	ds_write_b32 v19, v61 offset:7656
	s_waitcnt vmcnt(1)
	ds_write_b32 v19, v62 offset:7920
	s_waitcnt vmcnt(0)
	ds_write_b32 v19, v63 offset:8184
	s_lshl_b32 s0, s101, 16
	s_lshl_b32 s1, s100, 7
	s_add_u32 s0, s0, s1
	s_add_u32 s0, s34, s0
	s_addc_u32 s1, s35, 0
	s_waitcnt lgkmcnt(0)
	ds_read_b32 v64, v22
	ds_read_b32 v65, v22 offset:132
	ds_read_b32 v66, v22 offset:264
	ds_read_b32 v67, v22 offset:396
	ds_read_b32 v68, v22 offset:528
	ds_read_b32 v69, v22 offset:660
	ds_read_b32 v70, v22 offset:792
	ds_read_b32 v71, v22 offset:924
	ds_read_b32 v72, v22 offset:32
	ds_read_b32 v73, v22 offset:164
	ds_read_b32 v74, v22 offset:296
	ds_read_b32 v75, v22 offset:428
	ds_read_b32 v76, v22 offset:560
	ds_read_b32 v77, v22 offset:692
	ds_read_b32 v78, v22 offset:824
	ds_read_b32 v79, v22 offset:956
	ds_read_b32 v80, v22 offset:64
	ds_read_b32 v81, v22 offset:196
	ds_read_b32 v82, v22 offset:328
	ds_read_b32 v83, v22 offset:460
	ds_read_b32 v84, v22 offset:592
	ds_read_b32 v85, v22 offset:724
	ds_read_b32 v86, v22 offset:856
	ds_read_b32 v87, v22 offset:988
	ds_read_b32 v88, v22 offset:96
	ds_read_b32 v89, v22 offset:228
	ds_read_b32 v90, v22 offset:360
	ds_read_b32 v91, v22 offset:492
	ds_read_b32 v92, v22 offset:624
	ds_read_b32 v93, v22 offset:756
	ds_read_b32 v94, v22 offset:888
	ds_read_b32 v95, v22 offset:1020
	s_waitcnt lgkmcnt(15)
	v_cvt_pk_bf16_f32 v96, v64, v65
	v_cvt_pk_bf16_f32 v97, v66, v67
	v_cvt_pk_bf16_f32 v98, v68, v69
	v_cvt_pk_bf16_f32 v99, v70, v71
	global_store_dwordx4 v24, v[96:99], s[0:1]
	s_add_u32 s0, s0, 0x4000
	s_addc_u32 s1, s1, 0
	s_waitcnt lgkmcnt(15)
	v_cvt_pk_bf16_f32 v100, v72, v73
	v_cvt_pk_bf16_f32 v101, v74, v75
	v_cvt_pk_bf16_f32 v102, v76, v77
	v_cvt_pk_bf16_f32 v103, v78, v79
	global_store_dwordx4 v24, v[100:103], s[0:1]
	s_add_u32 s0, s0, 0x4000
	s_addc_u32 s1, s1, 0
	s_waitcnt lgkmcnt(8)
	v_cvt_pk_bf16_f32 v104, v80, v81
	v_cvt_pk_bf16_f32 v105, v82, v83
	v_cvt_pk_bf16_f32 v106, v84, v85
	v_cvt_pk_bf16_f32 v107, v86, v87
	global_store_dwordx4 v24, v[104:107], s[0:1]
	s_add_u32 s0, s0, 0x4000
	s_addc_u32 s1, s1, 0
	s_waitcnt lgkmcnt(0)
	v_cvt_pk_bf16_f32 v108, v88, v89
	v_cvt_pk_bf16_f32 v109, v90, v91
	v_cvt_pk_bf16_f32 v110, v92, v93
	v_cvt_pk_bf16_f32 v111, v94, v95
	global_store_dwordx4 v24, v[108:111], s[0:1]
; __device__ __forceinline__ void transpose_item(const float* W, int K, int N, bf16_t* WT, int n0src, int n0dst, int k0, LAS float* scr, int lane) {
;     ...
;     asm volatile("s_waitcnt lgkmcnt(0)" ::: "memory");
; }
.Ltr_end_a1:
.Ltr_fin_a:
	s_mov_b64 exec, s[38:39]

; #define LAS __attribute__((address_space(3)))
; __device__ __forceinline__ void transpose_item(const float* W, int K, int N, bf16_t* WT, int n0src, int n0dst, int k0, LAS float* scr, int lane) {
;     float v[32];
; #pragma unroll
;     for (int i = 0; i < 32; ++i) { const int kk = 2 * i + (lane >> 5); v[i] = W[(size_t)(k0 + kk) * N + n0src + (lane & 31)]; }
; #pragma unroll
;     for (int i = 0; i < 32; ++i) { const int kk = 2 * i + (lane >> 5); scr[kk * 33 + (lane & 31)] = v[i]; }
; __device__ __forceinline__ void prologue(const Params& p, LAS unsigned char* lds) {
;     ...
;             if (r < 4 * I_W2) { const int mi = r / I_W2; r -= mi * I_W2; const int kb = r / 32, nb = r % 32;
;                 transpose_item(p.in[I_FFNWOUT] + (size_t)mi * DFF * D, DFF, D, (bf16_t*)(ws + WS_W2T + mi * SZ_W2T), nb * 32, nb * 32, kb * 64, scr, lane); continue; }
.Ltr_loop_b0:
	s_add_i32 s40, s98, 0x380
	s_cmpk_ge_u32 s40, 0x580
	s_cbranch_scc1 .Ltr_single_b0
	s_lshr_b32 s100, s98, 5
	s_and_b32 s101, s98, 31
	s_lshl_b32 s0, s100, 18
	s_lshl_b32 s1, s101, 7
	s_add_u32 s0, s0, s1
	s_add_u32 s0, s32, s0
	s_addc_u32 s1, s33, 0
	global_load_dword v32, v23, s[0:1] nt
	s_add_u32 s0, s0, 0x2000
	s_addc_u32 s1, s1, 0
	global_load_dword v33, v23, s[0:1] nt
	s_add_u32 s0, s0, 0x2000
	s_addc_u32 s1, s1, 0
	global_load_dword v34, v23, s[0:1] nt
	s_add_u32 s0, s0, 0x2000
	s_addc_u32 s1, s1, 0
	global_load_dword v35, v23, s[0:1] nt
	s_add_u32 s0, s0, 0x2000
	s_addc_u32 s1, s1, 0
	global_load_dword v36, v23, s[0:1] nt
	s_add_u32 s0, s0, 0x2000
	s_addc_u32 s1, s1, 0
	global_load_dword v37, v23, s[0:1] nt
	s_add_u32 s0, s0, 0x2000
	s_addc_u32 s1, s1, 0
	global_load_dword v38, v23, s[0:1] nt
	s_add_u32 s0, s0, 0x2000
	s_addc_u32 s1, s1, 0
	global_load_dword v39, v23, s[0:1] nt
	s_add_u32 s0, s0, 0x2000
	s_addc_u32 s1, s1, 0
	global_load_dword v40, v23, s[0:1] nt
	s_add_u32 s0, s0, 0x2000
	s_addc_u32 s1, s1, 0
	global_load_dword v41, v23, s[0:1] nt
	s_add_u32 s0, s0, 0x2000
	s_addc_u32 s1, s1, 0
	global_load_dword v42, v23, s[0:1] nt
	s_add_u32 s0, s0, 0x2000
	s_addc_u32 s1, s1, 0
	global_load_dword v43, v23, s[0:1] nt
	s_add_u32 s0, s0, 0x2000
	s_addc_u32 s1, s1, 0
	global_load_dword v44, v23, s[0:1] nt
	s_add_u32 s0, s0, 0x2000
	s_addc_u32 s1, s1, 0
	global_load_dword v45, v23, s[0:1] nt
	s_add_u32 s0, s0, 0x2000
	s_addc_u32 s1, s1, 0
	global_load_dword v46, v23, s[0:1] nt
	s_add_u32 s0, s0, 0x2000
	s_addc_u32 s1, s1, 0
	global_load_dword v47, v23, s[0:1] nt
	s_add_u32 s0, s0, 0x2000
	s_addc_u32 s1, s1, 0
	global_load_dword v48, v23, s[0:1] nt
	s_add_u32 s0, s0, 0x2000
	s_addc_u32 s1, s1, 0
	global_load_dword v49, v23, s[0:1] nt
	s_add_u32 s0, s0, 0x2000
	s_addc_u32 s1, s1, 0
	global_load_dword v50, v23, s[0:1] nt
	s_add_u32 s0, s0, 0x2000
	s_addc_u32 s1, s1, 0
	global_load_dword v51, v23, s[0:1] nt
	s_add_u32 s0, s0, 0x2000
	s_addc_u32 s1, s1, 0
	global_load_dword v52, v23, s[0:1] nt
	s_add_u32 s0, s0, 0x2000
	s_addc_u32 s1, s1, 0
	global_load_dword v53, v23, s[0:1] nt
	s_add_u32 s0, s0, 0x2000
	s_addc_u32 s1, s1, 0
	global_load_dword v54, v23, s[0:1] nt
	s_add_u32 s0, s0, 0x2000
	s_addc_u32 s1, s1, 0
	global_load_dword v55, v23, s[0:1] nt
	s_add_u32 s0, s0, 0x2000
	s_addc_u32 s1, s1, 0
	global_load_dword v56, v23, s[0:1] nt
	s_add_u32 s0, s0, 0x2000
	s_addc_u32 s1, s1, 0
	global_load_dword v57, v23, s[0:1] nt
	s_add_u32 s0, s0, 0x2000
	s_addc_u32 s1, s1, 0
	global_load_dword v58, v23, s[0:1] nt
	s_add_u32 s0, s0, 0x2000
	s_addc_u32 s1, s1, 0
	global_load_dword v59, v23, s[0:1] nt
	s_add_u32 s0, s0, 0x2000
	s_addc_u32 s1, s1, 0
	global_load_dword v60, v23, s[0:1] nt
	s_add_u32 s0, s0, 0x2000
	s_addc_u32 s1, s1, 0
	global_load_dword v61, v23, s[0:1] nt
	s_add_u32 s0, s0, 0x2000
	s_addc_u32 s1, s1, 0
	global_load_dword v62, v23, s[0:1] nt
	s_add_u32 s0, s0, 0x2000
	s_addc_u32 s1, s1, 0
	global_load_dword v63, v23, s[0:1] nt
	s_lshr_b32 s41, s40, 5
	s_and_b32 s42, s40, 31
	s_lshl_b32 s0, s41, 18
	s_lshl_b32 s1, s42, 7
	s_add_u32 s0, s0, s1
	s_add_u32 s0, s32, s0
	s_addc_u32 s1, s33, 0
	global_load_dword v112, v23, s[0:1] nt
	s_add_u32 s0, s0, 0x2000
	s_addc_u32 s1, s1, 0
	global_load_dword v113, v23, s[0:1] nt
	s_add_u32 s0, s0, 0x2000
	s_addc_u32 s1, s1, 0
	global_load_dword v114, v23, s[0:1] nt
	s_add_u32 s0, s0, 0x2000
	s_addc_u32 s1, s1, 0
	global_load_dword v115, v23, s[0:1] nt
	s_add_u32 s0, s0, 0x2000
	s_addc_u32 s1, s1, 0
	global_load_dword v116, v23, s[0:1] nt
	s_add_u32 s0, s0, 0x2000
	s_addc_u32 s1, s1, 0
	global_load_dword v117, v23, s[0:1] nt
	s_add_u32 s0, s0, 0x2000
	s_addc_u32 s1, s1, 0
	global_load_dword v118, v23, s[0:1] nt
	s_add_u32 s0, s0, 0x2000
	s_addc_u32 s1, s1, 0
	global_load_dword v119, v23, s[0:1] nt
	s_add_u32 s0, s0, 0x2000
	s_addc_u32 s1, s1, 0
	global_load_dword v120, v23, s[0:1] nt
	s_add_u32 s0, s0, 0x2000
	s_addc_u32 s1, s1, 0
	global_load_dword v121, v23, s[0:1] nt
	s_add_u32 s0, s0, 0x2000
	s_addc_u32 s1, s1, 0
	global_load_dword v122, v23, s[0:1] nt
	s_add_u32 s0, s0, 0x2000
	s_addc_u32 s1, s1, 0
	global_load_dword v123, v23, s[0:1] nt
	s_add_u32 s0, s0, 0x2000
	s_addc_u32 s1, s1, 0
	global_load_dword v124, v23, s[0:1] nt
	s_add_u32 s0, s0, 0x2000
	s_addc_u32 s1, s1, 0
	global_load_dword v125, v23, s[0:1] nt
	s_add_u32 s0, s0, 0x2000
	s_addc_u32 s1, s1, 0
	global_load_dword v126, v23, s[0:1] nt
	s_add_u32 s0, s0, 0x2000
	s_addc_u32 s1, s1, 0
	global_load_dword v127, v23, s[0:1] nt
	s_add_u32 s0, s0, 0x2000
	s_addc_u32 s1, s1, 0
	global_load_dword v128, v23, s[0:1] nt
	s_add_u32 s0, s0, 0x2000
	s_addc_u32 s1, s1, 0
	global_load_dword v129, v23, s[0:1] nt
	s_add_u32 s0, s0, 0x2000
	s_addc_u32 s1, s1, 0
	global_load_dword v130, v23, s[0:1] nt
	s_add_u32 s0, s0, 0x2000
	s_addc_u32 s1, s1, 0
	global_load_dword v131, v23, s[0:1] nt
	s_add_u32 s0, s0, 0x2000
	s_addc_u32 s1, s1, 0
	global_load_dword v132, v23, s[0:1] nt
	s_add_u32 s0, s0, 0x2000
	s_addc_u32 s1, s1, 0
	global_load_dword v133, v23, s[0:1] nt
	s_add_u32 s0, s0, 0x2000
	s_addc_u32 s1, s1, 0
	global_load_dword v134, v23, s[0:1] nt
	s_add_u32 s0, s0, 0x2000
	s_addc_u32 s1, s1, 0
	global_load_dword v135, v23, s[0:1] nt
	s_add_u32 s0, s0, 0x2000
	s_addc_u32 s1, s1, 0
	global_load_dword v136, v23, s[0:1] nt
	s_add_u32 s0, s0, 0x2000
	s_addc_u32 s1, s1, 0
	global_load_dword v137, v23, s[0:1] nt
	s_add_u32 s0, s0, 0x2000
	s_addc_u32 s1, s1, 0
	global_load_dword v138, v23, s[0:1] nt
	s_add_u32 s0, s0, 0x2000
	s_addc_u32 s1, s1, 0
	global_load_dword v139, v23, s[0:1] nt
	s_add_u32 s0, s0, 0x2000
	s_addc_u32 s1, s1, 0
	global_load_dword v140, v23, s[0:1] nt
	s_add_u32 s0, s0, 0x2000
	s_addc_u32 s1, s1, 0
	global_load_dword v141, v23, s[0:1] nt
	s_add_u32 s0, s0, 0x2000
	s_addc_u32 s1, s1, 0
	global_load_dword v142, v23, s[0:1] nt
	s_add_u32 s0, s0, 0x2000
	s_addc_u32 s1, s1, 0
	global_load_dword v143, v23, s[0:1] nt
	s_waitcnt vmcnt(63)
; #define LAS __attribute__((address_space(3)))
; __device__ __forceinline__ unsigned cvt_pk_bf16(float lo, float hi) { unsigned r; asm volatile("v_cvt_pk_bf16_f32 %0, %1, %2" : "=v"(r) : "v"(lo), "v"(hi)); return r; }
; #define ST16(grp, p, v) do { if ((NTG >> (grp)) & 1) NT16(p, v); else PL16(p, v); } while (0)
; __device__ __forceinline__ void transpose_item(const float* W, int K, int N, bf16_t* WT, int n0src, int n0dst, int k0, LAS float* scr, int lane) {
;     ...
;     for (int i = 0; i < 32; ++i) { const int kk = 2 * i + (lane >> 5); v[i] = W[(size_t)(k0 + kk) * N + n0src + (lane & 31)]; }
; #pragma unroll
;     for (int i = 0; i < 32; ++i) { const int kk = 2 * i + (lane >> 5); scr[kk * 33 + (lane & 31)] = v[i]; }
;     asm volatile("s_waitcnt lgkmcnt(0)" ::: "memory");
;     const int c = lane & 7;
; #pragma unroll
;     for (int j = 0; j < 4; ++j) { const int n = (lane >> 3) + 8 * j; const LAS float* s = scr + (8 * c) * 33 + n;
;         u32x4 o; o.x = cvt_pk_bf16(s[0 * 33], s[1 * 33]); o.y = cvt_pk_bf16(s[2 * 33], s[3 * 33]); o.z = cvt_pk_bf16(s[4 * 33], s[5 * 33]); o.w = cvt_pk_bf16(s[6 * 33], s[7 * 33]);
;         ST16(6, WT + (size_t)(n0dst + n) * K + k0 + 8 * c, o); }
	ds_write_b32 v19, v32
	s_waitcnt vmcnt(62)
	ds_write_b32 v19, v33 offset:264
	s_waitcnt vmcnt(61)
	ds_write_b32 v19, v34 offset:528
	s_waitcnt vmcnt(60)
	ds_write_b32 v19, v35 offset:792
	s_waitcnt vmcnt(59)
	ds_write_b32 v19, v36 offset:1056
	s_waitcnt vmcnt(58)
	ds_write_b32 v19, v37 offset:1320
	s_waitcnt vmcnt(57)
	ds_write_b32 v19, v38 offset:1584
	s_waitcnt vmcnt(56)
	ds_write_b32 v19, v39 offset:1848
	s_waitcnt vmcnt(55)
	ds_write_b32 v19, v40 offset:2112
	s_waitcnt vmcnt(54)
	ds_write_b32 v19, v41 offset:2376
	s_waitcnt vmcnt(53)
	ds_write_b32 v19, v42 offset:2640
	s_waitcnt vmcnt(52)
	ds_write_b32 v19, v43 offset:2904
	s_waitcnt vmcnt(51)
	ds_write_b32 v19, v44 offset:3168
	s_waitcnt vmcnt(50)
	ds_write_b32 v19, v45 offset:3432
	s_waitcnt vmcnt(49)
	ds_write_b32 v19, v46 offset:3696
	s_waitcnt vmcnt(48)
	ds_write_b32 v19, v47 offset:3960
	s_waitcnt vmcnt(47)
	ds_write_b32 v19, v48 offset:4224
	s_waitcnt vmcnt(46)
	ds_write_b32 v19, v49 offset:4488
	s_waitcnt vmcnt(45)
	ds_write_b32 v19, v50 offset:4752
	s_waitcnt vmcnt(44)
	ds_write_b32 v19, v51 offset:5016
	s_waitcnt vmcnt(43)
	ds_write_b32 v19, v52 offset:5280
	s_waitcnt vmcnt(42)
	ds_write_b32 v19, v53 offset:5544
	s_waitcnt vmcnt(41)
	ds_write_b32 v19, v54 offset:5808
	s_waitcnt vmcnt(40)
	ds_write_b32 v19, v55 offset:6072
	s_waitcnt vmcnt(39)
	ds_write_b32 v19, v56 offset:6336
	s_waitcnt vmcnt(38)
	ds_write_b32 v19, v57 offset:6600
	s_waitcnt vmcnt(37)
	ds_write_b32 v19, v58 offset:6864
	s_waitcnt vmcnt(36)
	ds_write_b32 v19, v59 offset:7128
	s_waitcnt vmcnt(35)
	ds_write_b32 v19, v60 offset:7392
	s_waitcnt vmcnt(34)
	ds_write_b32 v19, v61 offset:7656
	s_waitcnt vmcnt(33)
	ds_write_b32 v19, v62 offset:7920
	s_waitcnt vmcnt(32)
	ds_write_b32 v19, v63 offset:8184
	s_mul_i32 s0, s101, 0x2c000
	s_lshl_b32 s1, s100, 7
	s_add_u32 s0, s0, s1
	s_add_u32 s0, s34, s0
	s_addc_u32 s1, s35, 0
	s_waitcnt lgkmcnt(0)
	ds_read_b32 v64, v22
	ds_read_b32 v65, v22 offset:132
	ds_read_b32 v66, v22 offset:264
	ds_read_b32 v67, v22 offset:396
	ds_read_b32 v68, v22 offset:528
	ds_read_b32 v69, v22 offset:660
	ds_read_b32 v70, v22 offset:792
	ds_read_b32 v71, v22 offset:924
	ds_read_b32 v72, v22 offset:32
	ds_read_b32 v73, v22 offset:164
	ds_read_b32 v74, v22 offset:296
	ds_read_b32 v75, v22 offset:428
	ds_read_b32 v76, v22 offset:560
	ds_read_b32 v77, v22 offset:692
	ds_read_b32 v78, v22 offset:824
	ds_read_b32 v79, v22 offset:956
	ds_read_b32 v80, v22 offset:64
	ds_read_b32 v81, v22 offset:196
	ds_read_b32 v82, v22 offset:328
	ds_read_b32 v83, v22 offset:460
	ds_read_b32 v84, v22 offset:592
	ds_read_b32 v85, v22 offset:724
	ds_read_b32 v86, v22 offset:856
	ds_read_b32 v87, v22 offset:988
	ds_read_b32 v88, v22 offset:96
	ds_read_b32 v89, v22 offset:228
	ds_read_b32 v90, v22 offset:360
	ds_read_b32 v91, v22 offset:492
	ds_read_b32 v92, v22 offset:624
	ds_read_b32 v93, v22 offset:756
	ds_read_b32 v94, v22 offset:888
	ds_read_b32 v95, v22 offset:1020
	s_waitcnt lgkmcnt(15)
	v_cvt_pk_bf16_f32 v96, v64, v65
	v_cvt_pk_bf16_f32 v97, v66, v67
	v_cvt_pk_bf16_f32 v98, v68, v69
	v_cvt_pk_bf16_f32 v99, v70, v71
	global_store_dwordx4 v24, v[96:99], s[0:1]
	s_add_u32 s0, s0, 0xb000
	s_addc_u32 s1, s1, 0
	s_waitcnt lgkmcnt(15)
	v_cvt_pk_bf16_f32 v100, v72, v73
	v_cvt_pk_bf16_f32 v101, v74, v75
	v_cvt_pk_bf16_f32 v102, v76, v77
	v_cvt_pk_bf16_f32 v103, v78, v79
	global_store_dwordx4 v24, v[100:103], s[0:1]
	s_add_u32 s0, s0, 0xb000
	s_addc_u32 s1, s1, 0
	s_waitcnt lgkmcnt(8)
	v_cvt_pk_bf16_f32 v104, v80, v81
	v_cvt_pk_bf16_f32 v105, v82, v83
	v_cvt_pk_bf16_f32 v106, v84, v85
	v_cvt_pk_bf16_f32 v107, v86, v87
	global_store_dwordx4 v24, v[104:107], s[0:1]
	s_add_u32 s0, s0, 0xb000
	s_addc_u32 s1, s1, 0
	s_waitcnt lgkmcnt(0)
	v_cvt_pk_bf16_f32 v108, v88, v89
	v_cvt_pk_bf16_f32 v109, v90, v91
	v_cvt_pk_bf16_f32 v110, v92, v93
	v_cvt_pk_bf16_f32 v111, v94, v95
	global_store_dwordx4 v24, v[108:111], s[0:1]
	s_waitcnt vmcnt(31)
	ds_write_b32 v19, v112
	s_waitcnt vmcnt(30)
	ds_write_b32 v19, v113 offset:264
	s_waitcnt vmcnt(29)
	ds_write_b32 v19, v114 offset:528
	s_waitcnt vmcnt(28)
	ds_write_b32 v19, v115 offset:792
	s_waitcnt vmcnt(27)
	ds_write_b32 v19, v116 offset:1056
	s_waitcnt vmcnt(26)
	ds_write_b32 v19, v117 offset:1320
	s_waitcnt vmcnt(25)
	ds_write_b32 v19, v118 offset:1584
	s_waitcnt vmcnt(24)
	ds_write_b32 v19, v119 offset:1848
	s_waitcnt vmcnt(23)
	ds_write_b32 v19, v120 offset:2112
	s_waitcnt vmcnt(22)
	ds_write_b32 v19, v121 offset:2376
	s_waitcnt vmcnt(21)
	ds_write_b32 v19, v122 offset:2640
	s_waitcnt vmcnt(20)
	ds_write_b32 v19, v123 offset:2904
	s_waitcnt vmcnt(19)
	ds_write_b32 v19, v124 offset:3168
	s_waitcnt vmcnt(18)
	ds_write_b32 v19, v125 offset:3432
	s_waitcnt vmcnt(17)
	ds_write_b32 v19, v126 offset:3696
	s_waitcnt vmcnt(16)
	ds_write_b32 v19, v127 offset:3960
	s_waitcnt vmcnt(15)
	ds_write_b32 v19, v128 offset:4224
	s_waitcnt vmcnt(14)
	ds_write_b32 v19, v129 offset:4488
	s_waitcnt vmcnt(13)
	ds_write_b32 v19, v130 offset:4752
	s_waitcnt vmcnt(12)
	ds_write_b32 v19, v131 offset:5016
	s_waitcnt vmcnt(11)
	ds_write_b32 v19, v132 offset:5280
	s_waitcnt vmcnt(10)
	ds_write_b32 v19, v133 offset:5544
	s_waitcnt vmcnt(9)
	ds_write_b32 v19, v134 offset:5808
	s_waitcnt vmcnt(8)
	ds_write_b32 v19, v135 offset:6072
	s_waitcnt vmcnt(7)
	ds_write_b32 v19, v136 offset:6336
	s_waitcnt vmcnt(6)
	ds_write_b32 v19, v137 offset:6600
	s_waitcnt vmcnt(5)
	ds_write_b32 v19, v138 offset:6864
	s_waitcnt vmcnt(4)
	ds_write_b32 v19, v139 offset:7128
	s_waitcnt vmcnt(3)
	ds_write_b32 v19, v140 offset:7392
	s_waitcnt vmcnt(2)
	ds_write_b32 v19, v141 offset:7656
	s_waitcnt vmcnt(1)
	ds_write_b32 v19, v142 offset:7920
	s_waitcnt vmcnt(0)
; #define LAS __attribute__((address_space(3)))
; __device__ __forceinline__ unsigned cvt_pk_bf16(float lo, float hi) { unsigned r; asm volatile("v_cvt_pk_bf16_f32 %0, %1, %2" : "=v"(r) : "v"(lo), "v"(hi)); return r; }
; #define ST16(grp, p, v) do { if ((NTG >> (grp)) & 1) NT16(p, v); else PL16(p, v); } while (0)
; __device__ __forceinline__ void transpose_item(const float* W, int K, int N, bf16_t* WT, int n0src, int n0dst, int k0, LAS float* scr, int lane) {
;     ...
;     asm volatile("s_waitcnt lgkmcnt(0)" ::: "memory");
;     const int c = lane & 7;
; #pragma unroll
;     for (int j = 0; j < 4; ++j) { const int n = (lane >> 3) + 8 * j; const LAS float* s = scr + (8 * c) * 33 + n;
;         u32x4 o; o.x = cvt_pk_bf16(s[0 * 33], s[1 * 33]); o.y = cvt_pk_bf16(s[2 * 33], s[3 * 33]); o.z = cvt_pk_bf16(s[4 * 33], s[5 * 33]); o.w = cvt_pk_bf16(s[6 * 33], s[7 * 33]);
;         ST16(6, WT + (size_t)(n0dst + n) * K + k0 + 8 * c, o); }
;     asm volatile("s_waitcnt lgkmcnt(0)" ::: "memory");
; }
	ds_write_b32 v19, v143 offset:8184
	s_mul_i32 s0, s42, 0x2c000
	s_lshl_b32 s1, s41, 7
	s_add_u32 s0, s0, s1
	s_add_u32 s0, s34, s0
	s_addc_u32 s1, s35, 0
	s_waitcnt lgkmcnt(0)
	ds_read_b32 v64, v22
	ds_read_b32 v65, v22 offset:132
	ds_read_b32 v66, v22 offset:264
	ds_read_b32 v67, v22 offset:396
	ds_read_b32 v68, v22 offset:528
	ds_read_b32 v69, v22 offset:660
	ds_read_b32 v70, v22 offset:792
	ds_read_b32 v71, v22 offset:924
	ds_read_b32 v72, v22 offset:32
	ds_read_b32 v73, v22 offset:164
	ds_read_b32 v74, v22 offset:296
	ds_read_b32 v75, v22 offset:428
	ds_read_b32 v76, v22 offset:560
	ds_read_b32 v77, v22 offset:692
	ds_read_b32 v78, v22 offset:824
	ds_read_b32 v79, v22 offset:956
	ds_read_b32 v80, v22 offset:64
	ds_read_b32 v81, v22 offset:196
	ds_read_b32 v82, v22 offset:328
	ds_read_b32 v83, v22 offset:460
	ds_read_b32 v84, v22 offset:592
	ds_read_b32 v85, v22 offset:724
	ds_read_b32 v86, v22 offset:856
	ds_read_b32 v87, v22 offset:988
	ds_read_b32 v88, v22 offset:96
	ds_read_b32 v89, v22 offset:228
	ds_read_b32 v90, v22 offset:360
	ds_read_b32 v91, v22 offset:492
	ds_read_b32 v92, v22 offset:624
	ds_read_b32 v93, v22 offset:756
	ds_read_b32 v94, v22 offset:888
	ds_read_b32 v95, v22 offset:1020
	s_waitcnt lgkmcnt(15)
	v_cvt_pk_bf16_f32 v96, v64, v65
	v_cvt_pk_bf16_f32 v97, v66, v67
	v_cvt_pk_bf16_f32 v98, v68, v69
	v_cvt_pk_bf16_f32 v99, v70, v71
	global_store_dwordx4 v24, v[96:99], s[0:1]
	s_add_u32 s0, s0, 0xb000
	s_addc_u32 s1, s1, 0
	s_waitcnt lgkmcnt(15)
	v_cvt_pk_bf16_f32 v100, v72, v73
	v_cvt_pk_bf16_f32 v101, v74, v75
	v_cvt_pk_bf16_f32 v102, v76, v77
	v_cvt_pk_bf16_f32 v103, v78, v79
	global_store_dwordx4 v24, v[100:103], s[0:1]
	s_add_u32 s0, s0, 0xb000
	s_addc_u32 s1, s1, 0
	s_waitcnt lgkmcnt(8)
	v_cvt_pk_bf16_f32 v104, v80, v81
	v_cvt_pk_bf16_f32 v105, v82, v83
	v_cvt_pk_bf16_f32 v106, v84, v85
	v_cvt_pk_bf16_f32 v107, v86, v87
	global_store_dwordx4 v24, v[104:107], s[0:1]
	s_add_u32 s0, s0, 0xb000
	s_addc_u32 s1, s1, 0
	s_waitcnt lgkmcnt(0)
	v_cvt_pk_bf16_f32 v108, v88, v89
	v_cvt_pk_bf16_f32 v109, v90, v91
	v_cvt_pk_bf16_f32 v110, v92, v93
	v_cvt_pk_bf16_f32 v111, v94, v95
	global_store_dwordx4 v24, v[108:111], s[0:1]
	s_add_i32 s98, s98, 0x700
	s_cmpk_lt_u32 s98, 0x580
	s_cbranch_scc1 .Ltr_loop_b0
	s_branch .Ltr_end_b0
; #define LAS __attribute__((address_space(3)))
; __device__ __forceinline__ unsigned cvt_pk_bf16(float lo, float hi) { unsigned r; asm volatile("v_cvt_pk_bf16_f32 %0, %1, %2" : "=v"(r) : "v"(lo), "v"(hi)); return r; }
; #define ST16(grp, p, v) do { if ((NTG >> (grp)) & 1) NT16(p, v); else PL16(p, v); } while (0)
; __device__ __forceinline__ void transpose_item(const float* W, int K, int N, bf16_t* WT, int n0src, int n0dst, int k0, LAS float* scr, int lane) {
;     float v[32];
; #pragma unroll
;     for (int i = 0; i < 32; ++i) { const int kk = 2 * i + (lane >> 5); v[i] = W[(size_t)(k0 + kk) * N + n0src + (lane & 31)]; }
; #pragma unroll
;     for (int i = 0; i < 32; ++i) { const int kk = 2 * i + (lane >> 5); scr[kk * 33 + (lane & 31)] = v[i]; }
;     asm volatile("s_waitcnt lgkmcnt(0)" ::: "memory");
;     const int c = lane & 7;
; #pragma unroll
;     for (int j = 0; j < 4; ++j) { const int n = (lane >> 3) + 8 * j; const LAS float* s = scr + (8 * c) * 33 + n;
;         u32x4 o; o.x = cvt_pk_bf16(s[0 * 33], s[1 * 33]); o.y = cvt_pk_bf16(s[2 * 33], s[3 * 33]); o.z = cvt_pk_bf16(s[4 * 33], s[5 * 33]); o.w = cvt_pk_bf16(s[6 * 33], s[7 * 33]);
;         ST16(6, WT + (size_t)(n0dst + n) * K + k0 + 8 * c, o); }
;     asm volatile("s_waitcnt lgkmcnt(0)" ::: "memory");
; }
.Ltr_single_b0:
	s_lshr_b32 s100, s98, 5
	s_and_b32 s101, s98, 31
	s_lshl_b32 s0, s100, 18
	s_lshl_b32 s1, s101, 7
	s_add_u32 s0, s0, s1
	s_add_u32 s0, s32, s0
	s_addc_u32 s1, s33, 0
	global_load_dword v32, v23, s[0:1] nt
	s_add_u32 s0, s0, 0x2000
	s_addc_u32 s1, s1, 0
	global_load_dword v33, v23, s[0:1] nt
	s_add_u32 s0, s0, 0x2000
	s_addc_u32 s1, s1, 0
	global_load_dword v34, v23, s[0:1] nt
	s_add_u32 s0, s0, 0x2000
	s_addc_u32 s1, s1, 0
	global_load_dword v35, v23, s[0:1] nt
	s_add_u32 s0, s0, 0x2000
	s_addc_u32 s1, s1, 0
	global_load_dword v36, v23, s[0:1] nt
	s_add_u32 s0, s0, 0x2000
	s_addc_u32 s1, s1, 0
	global_load_dword v37, v23, s[0:1] nt
	s_add_u32 s0, s0, 0x2000
	s_addc_u32 s1, s1, 0
	global_load_dword v38, v23, s[0:1] nt
	s_add_u32 s0, s0, 0x2000
	s_addc_u32 s1, s1, 0
	global_load_dword v39, v23, s[0:1] nt
	s_add_u32 s0, s0, 0x2000
	s_addc_u32 s1, s1, 0
	global_load_dword v40, v23, s[0:1] nt
	s_add_u32 s0, s0, 0x2000
	s_addc_u32 s1, s1, 0
	global_load_dword v41, v23, s[0:1] nt
	s_add_u32 s0, s0, 0x2000
	s_addc_u32 s1, s1, 0
	global_load_dword v42, v23, s[0:1] nt
	s_add_u32 s0, s0, 0x2000
	s_addc_u32 s1, s1, 0
	global_load_dword v43, v23, s[0:1] nt
	s_add_u32 s0, s0, 0x2000
	s_addc_u32 s1, s1, 0
	global_load_dword v44, v23, s[0:1] nt
	s_add_u32 s0, s0, 0x2000
	s_addc_u32 s1, s1, 0
	global_load_dword v45, v23, s[0:1] nt
	s_add_u32 s0, s0, 0x2000
	s_addc_u32 s1, s1, 0
	global_load_dword v46, v23, s[0:1] nt
	s_add_u32 s0, s0, 0x2000
	s_addc_u32 s1, s1, 0
	global_load_dword v47, v23, s[0:1] nt
	s_add_u32 s0, s0, 0x2000
	s_addc_u32 s1, s1, 0
	global_load_dword v48, v23, s[0:1] nt
	s_add_u32 s0, s0, 0x2000
	s_addc_u32 s1, s1, 0
	global_load_dword v49, v23, s[0:1] nt
	s_add_u32 s0, s0, 0x2000
	s_addc_u32 s1, s1, 0
	global_load_dword v50, v23, s[0:1] nt
	s_add_u32 s0, s0, 0x2000
	s_addc_u32 s1, s1, 0
	global_load_dword v51, v23, s[0:1] nt
	s_add_u32 s0, s0, 0x2000
	s_addc_u32 s1, s1, 0
	global_load_dword v52, v23, s[0:1] nt
	s_add_u32 s0, s0, 0x2000
	s_addc_u32 s1, s1, 0
	global_load_dword v53, v23, s[0:1] nt
	s_add_u32 s0, s0, 0x2000
	s_addc_u32 s1, s1, 0
	global_load_dword v54, v23, s[0:1] nt
	s_add_u32 s0, s0, 0x2000
	s_addc_u32 s1, s1, 0
	global_load_dword v55, v23, s[0:1] nt
	s_add_u32 s0, s0, 0x2000
	s_addc_u32 s1, s1, 0
	global_load_dword v56, v23, s[0:1] nt
	s_add_u32 s0, s0, 0x2000
	s_addc_u32 s1, s1, 0
	global_load_dword v57, v23, s[0:1] nt
	s_add_u32 s0, s0, 0x2000
	s_addc_u32 s1, s1, 0
	global_load_dword v58, v23, s[0:1] nt
	s_add_u32 s0, s0, 0x2000
	s_addc_u32 s1, s1, 0
	global_load_dword v59, v23, s[0:1] nt
	s_add_u32 s0, s0, 0x2000
	s_addc_u32 s1, s1, 0
	global_load_dword v60, v23, s[0:1] nt
	s_add_u32 s0, s0, 0x2000
	s_addc_u32 s1, s1, 0
	global_load_dword v61, v23, s[0:1] nt
	s_add_u32 s0, s0, 0x2000
	s_addc_u32 s1, s1, 0
	global_load_dword v62, v23, s[0:1] nt
	s_add_u32 s0, s0, 0x2000
	s_addc_u32 s1, s1, 0
	global_load_dword v63, v23, s[0:1] nt
	s_waitcnt vmcnt(31)
	ds_write_b32 v19, v32
	s_waitcnt vmcnt(30)
	ds_write_b32 v19, v33 offset:264
	s_waitcnt vmcnt(29)
	ds_write_b32 v19, v34 offset:528
	s_waitcnt vmcnt(28)
	ds_write_b32 v19, v35 offset:792
	s_waitcnt vmcnt(27)
	ds_write_b32 v19, v36 offset:1056
	s_waitcnt vmcnt(26)
	ds_write_b32 v19, v37 offset:1320
	s_waitcnt vmcnt(25)
	ds_write_b32 v19, v38 offset:1584
	s_waitcnt vmcnt(24)
	ds_write_b32 v19, v39 offset:1848
	s_waitcnt vmcnt(23)
	ds_write_b32 v19, v40 offset:2112
	s_waitcnt vmcnt(22)
	ds_write_b32 v19, v41 offset:2376
	s_waitcnt vmcnt(21)
	ds_write_b32 v19, v42 offset:2640
	s_waitcnt vmcnt(20)
	ds_write_b32 v19, v43 offset:2904
	s_waitcnt vmcnt(19)
	ds_write_b32 v19, v44 offset:3168
	s_waitcnt vmcnt(18)
	ds_write_b32 v19, v45 offset:3432
	s_waitcnt vmcnt(17)
	ds_write_b32 v19, v46 offset:3696
	s_waitcnt vmcnt(16)
	ds_write_b32 v19, v47 offset:3960
	s_waitcnt vmcnt(15)
	ds_write_b32 v19, v48 offset:4224
	s_waitcnt vmcnt(14)
	ds_write_b32 v19, v49 offset:4488
	s_waitcnt vmcnt(13)
	ds_write_b32 v19, v50 offset:4752
	s_waitcnt vmcnt(12)
	ds_write_b32 v19, v51 offset:5016
	s_waitcnt vmcnt(11)
	ds_write_b32 v19, v52 offset:5280
	s_waitcnt vmcnt(10)
	ds_write_b32 v19, v53 offset:5544
	s_waitcnt vmcnt(9)
	ds_write_b32 v19, v54 offset:5808
	s_waitcnt vmcnt(8)
	ds_write_b32 v19, v55 offset:6072
	s_waitcnt vmcnt(7)
	ds_write_b32 v19, v56 offset:6336
	s_waitcnt vmcnt(6)
	ds_write_b32 v19, v57 offset:6600
	s_waitcnt vmcnt(5)
	ds_write_b32 v19, v58 offset:6864
	s_waitcnt vmcnt(4)
	ds_write_b32 v19, v59 offset:7128
	s_waitcnt vmcnt(3)
	ds_write_b32 v19, v60 offset:7392
	s_waitcnt vmcnt(2)
	ds_write_b32 v19, v61 offset:7656
	s_waitcnt vmcnt(1)
	ds_write_b32 v19, v62 offset:7920
	s_waitcnt vmcnt(0)
	ds_write_b32 v19, v63 offset:8184
	s_mul_i32 s0, s101, 0x2c000
	s_lshl_b32 s1, s100, 7
	s_add_u32 s0, s0, s1
	s_add_u32 s0, s34, s0
	s_addc_u32 s1, s35, 0
	s_waitcnt lgkmcnt(0)
	ds_read_b32 v64, v22
	ds_read_b32 v65, v22 offset:132
	ds_read_b32 v66, v22 offset:264
	ds_read_b32 v67, v22 offset:396
	ds_read_b32 v68, v22 offset:528
	ds_read_b32 v69, v22 offset:660
	ds_read_b32 v70, v22 offset:792
	ds_read_b32 v71, v22 offset:924
	ds_read_b32 v72, v22 offset:32
	ds_read_b32 v73, v22 offset:164
	ds_read_b32 v74, v22 offset:296
	ds_read_b32 v75, v22 offset:428
	ds_read_b32 v76, v22 offset:560
	ds_read_b32 v77, v22 offset:692
	ds_read_b32 v78, v22 offset:824
	ds_read_b32 v79, v22 offset:956
	ds_read_b32 v80, v22 offset:64
	ds_read_b32 v81, v22 offset:196
	ds_read_b32 v82, v22 offset:328
	ds_read_b32 v83, v22 offset:460
	ds_read_b32 v84, v22 offset:592
	ds_read_b32 v85, v22 offset:724
	ds_read_b32 v86, v22 offset:856
	ds_read_b32 v87, v22 offset:988
	ds_read_b32 v88, v22 offset:96
	ds_read_b32 v89, v22 offset:228
	ds_read_b32 v90, v22 offset:360
	ds_read_b32 v91, v22 offset:492
	ds_read_b32 v92, v22 offset:624
	ds_read_b32 v93, v22 offset:756
	ds_read_b32 v94, v22 offset:888
	ds_read_b32 v95, v22 offset:1020
	s_waitcnt lgkmcnt(15)
	v_cvt_pk_bf16_f32 v96, v64, v65
	v_cvt_pk_bf16_f32 v97, v66, v67
	v_cvt_pk_bf16_f32 v98, v68, v69
	v_cvt_pk_bf16_f32 v99, v70, v71
	global_store_dwordx4 v24, v[96:99], s[0:1]
	s_add_u32 s0, s0, 0xb000
	s_addc_u32 s1, s1, 0
	s_waitcnt lgkmcnt(15)
	v_cvt_pk_bf16_f32 v100, v72, v73
	v_cvt_pk_bf16_f32 v101, v74, v75
	v_cvt_pk_bf16_f32 v102, v76, v77
	v_cvt_pk_bf16_f32 v103, v78, v79
	global_store_dwordx4 v24, v[100:103], s[0:1]
	s_add_u32 s0, s0, 0xb000
	s_addc_u32 s1, s1, 0
	s_waitcnt lgkmcnt(8)
	v_cvt_pk_bf16_f32 v104, v80, v81
	v_cvt_pk_bf16_f32 v105, v82, v83
	v_cvt_pk_bf16_f32 v106, v84, v85
	v_cvt_pk_bf16_f32 v107, v86, v87
	global_store_dwordx4 v24, v[104:107], s[0:1]
	s_add_u32 s0, s0, 0xb000
	s_addc_u32 s1, s1, 0
	s_waitcnt lgkmcnt(0)
	v_cvt_pk_bf16_f32 v108, v88, v89
	v_cvt_pk_bf16_f32 v109, v90, v91
	v_cvt_pk_bf16_f32 v110, v92, v93
	v_cvt_pk_bf16_f32 v111, v94, v95
	global_store_dwordx4 v24, v[108:111], s[0:1]
.Ltr_end_b0:
.Ltr_fin_b:
	s_mov_b64 exec, s[38:39]

; #define LAS __attribute__((address_space(3)))
; __device__ __forceinline__ unsigned cvt_pk_bf16(float lo, float hi) { unsigned r; asm volatile("v_cvt_pk_bf16_f32 %0, %1, %2" : "=v"(r) : "v"(lo), "v"(hi)); return r; }
; #define ST16(grp, p, v) do { if ((NTG >> (grp)) & 1) NT16(p, v); else PL16(p, v); } while (0)
; __device__ __forceinline__ void transpose_item(const float* W, int K, int N, bf16_t* WT, int n0src, int n0dst, int k0, LAS float* scr, int lane) {
;     float v[32];
; #pragma unroll
;     for (int i = 0; i < 32; ++i) { const int kk = 2 * i + (lane >> 5); v[i] = W[(size_t)(k0 + kk) * N + n0src + (lane & 31)]; }
; #pragma unroll
;     for (int i = 0; i < 32; ++i) { const int kk = 2 * i + (lane >> 5); scr[kk * 33 + (lane & 31)] = v[i]; }
;     asm volatile("s_waitcnt lgkmcnt(0)" ::: "memory");
;     const int c = lane & 7;
; #pragma unroll
;     for (int j = 0; j < 4; ++j) { const int n = (lane >> 3) + 8 * j; const LAS float* s = scr + (8 * c) * 33 + n;
;         u32x4 o; o.x = cvt_pk_bf16(s[0 * 33], s[1 * 33]); o.y = cvt_pk_bf16(s[2 * 33], s[3 * 33]); o.z = cvt_pk_bf16(s[4 * 33], s[5 * 33]); o.w = cvt_pk_bf16(s[6 * 33], s[7 * 33]);
;         ST16(6, WT + (size_t)(n0dst + n) * K + k0 + 8 * c, o); }
;     asm volatile("s_waitcnt lgkmcnt(0)" ::: "memory");
; }
.Ltr_single_c0:
	s_lshr_b32 s100, s98, 5
	s_and_b32 s101, s98, 31
	s_lshl_b32 s0, s100, 18
	s_lshl_b32 s1, s101, 7
	s_add_u32 s0, s0, s1
	s_add_u32 s0, s32, s0
	s_addc_u32 s1, s33, 0
	global_load_dword v32, v23, s[0:1] nt
	s_add_u32 s0, s0, 0x2000
	s_addc_u32 s1, s1, 0
	global_load_dword v33, v23, s[0:1] nt
	s_add_u32 s0, s0, 0x2000
	s_addc_u32 s1, s1, 0
	global_load_dword v34, v23, s[0:1] nt
	s_add_u32 s0, s0, 0x2000
	s_addc_u32 s1, s1, 0
	global_load_dword v35, v23, s[0:1] nt
	s_add_u32 s0, s0, 0x2000
	s_addc_u32 s1, s1, 0
	global_load_dword v36, v23, s[0:1] nt
	s_add_u32 s0, s0, 0x2000
	s_addc_u32 s1, s1, 0
	global_load_dword v37, v23, s[0:1] nt
	s_add_u32 s0, s0, 0x2000
	s_addc_u32 s1, s1, 0
	global_load_dword v38, v23, s[0:1] nt
	s_add_u32 s0, s0, 0x2000
	s_addc_u32 s1, s1, 0
	global_load_dword v39, v23, s[0:1] nt
	s_add_u32 s0, s0, 0x2000
	s_addc_u32 s1, s1, 0
	global_load_dword v40, v23, s[0:1] nt
	s_add_u32 s0, s0, 0x2000
	s_addc_u32 s1, s1, 0
	global_load_dword v41, v23, s[0:1] nt
	s_add_u32 s0, s0, 0x2000
	s_addc_u32 s1, s1, 0
	global_load_dword v42, v23, s[0:1] nt
	s_add_u32 s0, s0, 0x2000
	s_addc_u32 s1, s1, 0
	global_load_dword v43, v23, s[0:1] nt
	s_add_u32 s0, s0, 0x2000
	s_addc_u32 s1, s1, 0
	global_load_dword v44, v23, s[0:1] nt
	s_add_u32 s0, s0, 0x2000
	s_addc_u32 s1, s1, 0
	global_load_dword v45, v23, s[0:1] nt
	s_add_u32 s0, s0, 0x2000
	s_addc_u32 s1, s1, 0
	global_load_dword v46, v23, s[0:1] nt
	s_add_u32 s0, s0, 0x2000
	s_addc_u32 s1, s1, 0
	global_load_dword v47, v23, s[0:1] nt
	s_add_u32 s0, s0, 0x2000
	s_addc_u32 s1, s1, 0
	global_load_dword v48, v23, s[0:1] nt
	s_add_u32 s0, s0, 0x2000
	s_addc_u32 s1, s1, 0
	global_load_dword v49, v23, s[0:1] nt
	s_add_u32 s0, s0, 0x2000
	s_addc_u32 s1, s1, 0
	global_load_dword v50, v23, s[0:1] nt
	s_add_u32 s0, s0, 0x2000
	s_addc_u32 s1, s1, 0
	global_load_dword v51, v23, s[0:1] nt
	s_add_u32 s0, s0, 0x2000
	s_addc_u32 s1, s1, 0
	global_load_dword v52, v23, s[0:1] nt
	s_add_u32 s0, s0, 0x2000
	s_addc_u32 s1, s1, 0
	global_load_dword v53, v23, s[0:1] nt
	s_add_u32 s0, s0, 0x2000
	s_addc_u32 s1, s1, 0
	global_load_dword v54, v23, s[0:1] nt
	s_add_u32 s0, s0, 0x2000
	s_addc_u32 s1, s1, 0
	global_load_dword v55, v23, s[0:1] nt
	s_add_u32 s0, s0, 0x2000
	s_addc_u32 s1, s1, 0
	global_load_dword v56, v23, s[0:1] nt
	s_add_u32 s0, s0, 0x2000
	s_addc_u32 s1, s1, 0
	global_load_dword v57, v23, s[0:1] nt
	s_add_u32 s0, s0, 0x2000
	s_addc_u32 s1, s1, 0
	global_load_dword v58, v23, s[0:1] nt
	s_add_u32 s0, s0, 0x2000
	s_addc_u32 s1, s1, 0
	global_load_dword v59, v23, s[0:1] nt
	s_add_u32 s0, s0, 0x2000
	s_addc_u32 s1, s1, 0
	global_load_dword v60, v23, s[0:1] nt
	s_add_u32 s0, s0, 0x2000
	s_addc_u32 s1, s1, 0
	global_load_dword v61, v23, s[0:1] nt
	s_add_u32 s0, s0, 0x2000
	s_addc_u32 s1, s1, 0
	global_load_dword v62, v23, s[0:1] nt
	s_add_u32 s0, s0, 0x2000
	s_addc_u32 s1, s1, 0
	global_load_dword v63, v23, s[0:1] nt
	s_waitcnt vmcnt(31)
	ds_write_b32 v19, v32
	s_waitcnt vmcnt(30)
	ds_write_b32 v19, v33 offset:264
	s_waitcnt vmcnt(29)
	ds_write_b32 v19, v34 offset:528
	s_waitcnt vmcnt(28)
	ds_write_b32 v19, v35 offset:792
	s_waitcnt vmcnt(27)
	ds_write_b32 v19, v36 offset:1056
	s_waitcnt vmcnt(26)
	ds_write_b32 v19, v37 offset:1320
	s_waitcnt vmcnt(25)
	ds_write_b32 v19, v38 offset:1584
	s_waitcnt vmcnt(24)
	ds_write_b32 v19, v39 offset:1848
	s_waitcnt vmcnt(23)
	ds_write_b32 v19, v40 offset:2112
	s_waitcnt vmcnt(22)
	ds_write_b32 v19, v41 offset:2376
	s_waitcnt vmcnt(21)
	ds_write_b32 v19, v42 offset:2640
	s_waitcnt vmcnt(20)
	ds_write_b32 v19, v43 offset:2904
	s_waitcnt vmcnt(19)
	ds_write_b32 v19, v44 offset:3168
	s_waitcnt vmcnt(18)
	ds_write_b32 v19, v45 offset:3432
	s_waitcnt vmcnt(17)
	ds_write_b32 v19, v46 offset:3696
	s_waitcnt vmcnt(16)
	ds_write_b32 v19, v47 offset:3960
	s_waitcnt vmcnt(15)
	ds_write_b32 v19, v48 offset:4224
	s_waitcnt vmcnt(14)
	ds_write_b32 v19, v49 offset:4488
	s_waitcnt vmcnt(13)
	ds_write_b32 v19, v50 offset:4752
	s_waitcnt vmcnt(12)
	ds_write_b32 v19, v51 offset:5016
	s_waitcnt vmcnt(11)
	ds_write_b32 v19, v52 offset:5280
	s_waitcnt vmcnt(10)
	ds_write_b32 v19, v53 offset:5544
	s_waitcnt vmcnt(9)
	ds_write_b32 v19, v54 offset:5808
	s_waitcnt vmcnt(8)
	ds_write_b32 v19, v55 offset:6072
	s_waitcnt vmcnt(7)
	ds_write_b32 v19, v56 offset:6336
	s_waitcnt vmcnt(6)
	ds_write_b32 v19, v57 offset:6600
	s_waitcnt vmcnt(5)
	ds_write_b32 v19, v58 offset:6864
	s_waitcnt vmcnt(4)
	ds_write_b32 v19, v59 offset:7128
	s_waitcnt vmcnt(3)
	ds_write_b32 v19, v60 offset:7392
	s_waitcnt vmcnt(2)
	ds_write_b32 v19, v61 offset:7656
	s_waitcnt vmcnt(1)
	ds_write_b32 v19, v62 offset:7920
	s_waitcnt vmcnt(0)
	ds_write_b32 v19, v63 offset:8184
	s_mul_i32 s0, s101, 0x2c000
	s_lshl_b32 s1, s100, 7
	s_add_u32 s0, s0, s1
	s_add_u32 s0, s34, s0
	s_addc_u32 s1, s35, 0
	s_waitcnt lgkmcnt(0)
	ds_read_b32 v64, v22
	ds_read_b32 v65, v22 offset:132
	ds_read_b32 v66, v22 offset:264
	ds_read_b32 v67, v22 offset:396
	ds_read_b32 v68, v22 offset:528
	ds_read_b32 v69, v22 offset:660
	ds_read_b32 v70, v22 offset:792
	ds_read_b32 v71, v22 offset:924
	ds_read_b32 v72, v22 offset:32
	ds_read_b32 v73, v22 offset:164
	ds_read_b32 v74, v22 offset:296
	ds_read_b32 v75, v22 offset:428
	ds_read_b32 v76, v22 offset:560
	ds_read_b32 v77, v22 offset:692
	ds_read_b32 v78, v22 offset:824
	ds_read_b32 v79, v22 offset:956
	ds_read_b32 v80, v22 offset:64
	ds_read_b32 v81, v22 offset:196
	ds_read_b32 v82, v22 offset:328
	ds_read_b32 v83, v22 offset:460
	ds_read_b32 v84, v22 offset:592
	ds_read_b32 v85, v22 offset:724
	ds_read_b32 v86, v22 offset:856
	ds_read_b32 v87, v22 offset:988
	ds_read_b32 v88, v22 offset:96
	ds_read_b32 v89, v22 offset:228
	ds_read_b32 v90, v22 offset:360
	ds_read_b32 v91, v22 offset:492
	ds_read_b32 v92, v22 offset:624
	ds_read_b32 v93, v22 offset:756
	ds_read_b32 v94, v22 offset:888
	ds_read_b32 v95, v22 offset:1020
	s_waitcnt lgkmcnt(15)
	v_cvt_pk_bf16_f32 v96, v64, v65
	v_cvt_pk_bf16_f32 v97, v66, v67
	v_cvt_pk_bf16_f32 v98, v68, v69
	v_cvt_pk_bf16_f32 v99, v70, v71
	global_store_dwordx4 v24, v[96:99], s[0:1]
	s_add_u32 s0, s0, 0xb000
	s_addc_u32 s1, s1, 0
	s_waitcnt lgkmcnt(15)
	v_cvt_pk_bf16_f32 v100, v72, v73
	v_cvt_pk_bf16_f32 v101, v74, v75
	v_cvt_pk_bf16_f32 v102, v76, v77
	v_cvt_pk_bf16_f32 v103, v78, v79
	global_store_dwordx4 v24, v[100:103], s[0:1]
	s_add_u32 s0, s0, 0xb000
	s_addc_u32 s1, s1, 0
	s_waitcnt lgkmcnt(8)
	v_cvt_pk_bf16_f32 v104, v80, v81
	v_cvt_pk_bf16_f32 v105, v82, v83
	v_cvt_pk_bf16_f32 v106, v84, v85
	v_cvt_pk_bf16_f32 v107, v86, v87
	global_store_dwordx4 v24, v[104:107], s[0:1]
	s_add_u32 s0, s0, 0xb000
	s_addc_u32 s1, s1, 0
	s_waitcnt lgkmcnt(0)
	v_cvt_pk_bf16_f32 v108, v88, v89
	v_cvt_pk_bf16_f32 v109, v90, v91
	v_cvt_pk_bf16_f32 v110, v92, v93
	v_cvt_pk_bf16_f32 v111, v94, v95
	global_store_dwordx4 v24, v[108:111], s[0:1]
.Ltr_end_c0:
.Ltr_fin_c:
	s_mov_b64 exec, s[38:39]
